# GEMM loops: priority raise moved ahead of the barrier (s_setprio 1; s_barrier) so the first MFMA follows the release directly; identical code size
# baseline (speedup 1.0000x reference)
; #define PG8_STAGE(bufoff, gbase, voff) do { _Pragma("unroll") for (int _i = 0; _i < 2; ++_i) \
;         __builtin_amdgcn_global_load_lds((const unsigned*)((const char*)(gbase) + (voff)[_i]), (LAS unsigned*)(lds + (bufoff) + ldsw + _i * 8192), 16, 0, 0); } while (0)
; #define PG8_LDA(dst, b, h) do { _Pragma("unroll") for (int m = 0; m < 4; ++m) _Pragma("unroll") for (int k = 0; k < 2; ++k) dst[m][k] = *(const LAS bf16x8*)(lds + PG8_SA(b, h) + aoff + m * 2048 + k * 1024); } while (0)
; #define PG8_LDB(dst, b, h) do { _Pragma("unroll") for (int n = 0; n < 2; ++n) _Pragma("unroll") for (int k = 0; k < 2; ++k) dst[n][k] = *(const LAS bf16x8*)(lds + PG8_SB(b, h) + boff + n * 2048 + k * 1024); } while (0)
; #define PG8_MMA(ai, bj, At, Bt) do { __builtin_amdgcn_s_setprio(1); _Pragma("unroll") for (int m = 0; m < 4; ++m) _Pragma("unroll") for (int n = 0; n < 2; ++n) _Pragma("unroll") for (int k = 0; k < 2; ++k) \
;         acc[ai][bj][m][n] = __builtin_amdgcn_mfma_f32_16x16x32_bf16(Bt[n][k], At[m][k], acc[ai][bj][m][n], 0, 0, 0); __builtin_amdgcn_s_setprio(0); } while (0)
; #define PG8_WAIT_V(n) asm volatile("s_waitcnt vmcnt(" #n ")" ::: "memory")
; #define PG8_WAIT_L(n) asm volatile("s_waitcnt lgkmcnt(" #n ")" ::: "memory")
; #define PG8_BAR __builtin_amdgcn_s_barrier()
; #define PG8_SCHED __builtin_amdgcn_sched_barrier(0)
; template <class Epi, class Sched>
; __device__ __forceinline__ void gemm_phase(LAS unsigned char* lds, const Gemm g, const Sched& S, const Epi& E, const int wave_s) {
;     ...
;             const bool last = (t == nt - 2);
;             const char* a1 = cA + (size_t)(t + 1) * kstep;
;             const char* a2 = last ? nA : cA + (size_t)(t + 2) * kstep; const char* b2 = last ? nB : cB + (size_t)(t + 2) * kstep;
;             const char* a3 = a2 + kstep; const char* b3 = b2 + kstep;
;             PG8_LDB(B0, 0, 0); PG8_LDB(B1, 0, 1); PG8_SCHED; PG8_LDA(At, 0, 0); PG8_STAGE(PG8_SA(1, 1), a1 + hstepA, voffA);
;             PG8_WAIT_V(8); PG8_WAIT_L(0); PG8_BAR; PG8_MMA(0, 0, At, B0); PG8_MMA(0, 1, At, B1); PG8_BAR; PG8_SCHED;
;             PG8_LDA(At, 0, 1); PG8_STAGE(PG8_SB(0, 0), b2, voffB); PG8_STAGE(PG8_SB(0, 1), b2 + hstepB, voffB); PG8_STAGE(PG8_SA(0, 0), a2, voffA);
;             PG8_WAIT_V(8); PG8_WAIT_L(0); PG8_BAR; PG8_MMA(1, 0, At, B0); PG8_MMA(1, 1, At, B1); PG8_BAR; PG8_SCHED;
.LBB0_125:
	ds_read_b128 v[152:155], v149
	ds_read_b128 v[156:159], v149 offset:1024
	ds_read_b128 v[160:163], v149 offset:2048
	ds_read_b128 v[164:167], v149 offset:3072
	ds_read_b128 v[168:171], v150
	ds_read_b128 v[172:175], v150 offset:1024
	ds_read_b128 v[176:179], v150 offset:2048
	ds_read_b128 v[180:183], v150 offset:3072
	s_add_u32 s4, s44, 0xfffc0080
	s_addc_u32 s5, s45, -1
	s_cmp_eq_u32 s65, 12
	s_cselect_b32 s47, s29, s5
	s_cselect_b32 s46, s61, s4
	s_cselect_b32 s5, s27, s64
	s_cselect_b32 s4, s62, s63
	v_lshl_add_u64 v[144:145], s[44:45], 0, v[136:137]
	s_add_i32 m0, s33, 0xc000
	ds_read_b128 v[184:187], v151
	ds_read_b128 v[188:191], v151 offset:1024
	ds_read_b128 v[192:195], v151 offset:2048
	ds_read_b128 v[196:199], v151 offset:3072
	ds_read_b128 v[200:203], v151 offset:4096
	ds_read_b128 v[204:207], v151 offset:5120
	ds_read_b128 v[210:213], v151 offset:6144
	ds_read_b128 v[214:217], v151 offset:7168
	global_load_lds_dwordx4 v[144:145], off
	v_lshl_add_u64 v[144:145], s[44:45], 0, v[138:139]
	s_add_i32 m0, s33, 0xe000
	s_nop 0
	global_load_lds_dwordx4 v[144:145], off
	s_waitcnt vmcnt(8) lgkmcnt(0)
	s_setprio 1
	s_barrier
	v_mfma_f32_16x16x32_bf16 v[124:127], v[152:155], v[184:187], v[124:127]
	v_mfma_f32_16x16x32_bf16 v[120:123], v[160:163], v[184:187], v[120:123]
	v_mfma_f32_16x16x32_bf16 v[116:119], v[152:155], v[192:195], v[116:119]
	v_mfma_f32_16x16x32_bf16 v[108:111], v[160:163], v[192:195], v[108:111]
	v_mfma_f32_16x16x32_bf16 v[100:103], v[152:155], v[200:203], v[100:103]
	v_mfma_f32_16x16x32_bf16 v[92:95], v[160:163], v[200:203], v[92:95]
	v_mfma_f32_16x16x32_bf16 v[84:87], v[152:155], v[210:213], v[84:87]
	v_mfma_f32_16x16x32_bf16 v[76:79], v[160:163], v[210:213], v[76:79]
	v_mfma_f32_16x16x32_bf16 v[124:127], v[156:159], v[188:191], v[124:127]
	v_mfma_f32_16x16x32_bf16 v[120:123], v[164:167], v[188:191], v[120:123]
	v_mfma_f32_16x16x32_bf16 v[116:119], v[156:159], v[196:199], v[116:119]
	v_mfma_f32_16x16x32_bf16 v[108:111], v[164:167], v[196:199], v[108:111]
	v_mfma_f32_16x16x32_bf16 v[100:103], v[156:159], v[204:207], v[100:103]
	v_mfma_f32_16x16x32_bf16 v[92:95], v[164:167], v[204:207], v[92:95]
	v_mfma_f32_16x16x32_bf16 v[84:87], v[156:159], v[214:217], v[84:87]
	v_mfma_f32_16x16x32_bf16 v[76:79], v[164:167], v[214:217], v[76:79]
	s_setprio 0
	s_setprio 1
	v_mfma_f32_16x16x32_bf16 v[112:115], v[168:171], v[184:187], v[112:115]
	v_mfma_f32_16x16x32_bf16 v[104:107], v[176:179], v[184:187], v[104:107]
	v_mfma_f32_16x16x32_bf16 v[96:99], v[168:171], v[192:195], v[96:99]
	v_mfma_f32_16x16x32_bf16 v[88:91], v[176:179], v[192:195], v[88:91]
	v_mfma_f32_16x16x32_bf16 v[80:83], v[168:171], v[200:203], v[80:83]
	v_mfma_f32_16x16x32_bf16 v[72:75], v[176:179], v[200:203], v[72:75]
	v_mfma_f32_16x16x32_bf16 v[68:71], v[168:171], v[210:213], v[68:71]
	v_mfma_f32_16x16x32_bf16 v[64:67], v[176:179], v[210:213], v[64:67]
	v_mfma_f32_16x16x32_bf16 v[112:115], v[172:175], v[188:191], v[112:115]
	v_mfma_f32_16x16x32_bf16 v[104:107], v[180:183], v[188:191], v[104:107]
	v_mfma_f32_16x16x32_bf16 v[96:99], v[172:175], v[196:199], v[96:99]
	v_mfma_f32_16x16x32_bf16 v[88:91], v[180:183], v[196:199], v[88:91]
	v_mfma_f32_16x16x32_bf16 v[80:83], v[172:175], v[204:207], v[80:83]
	v_mfma_f32_16x16x32_bf16 v[72:75], v[180:183], v[204:207], v[72:75]
	v_mfma_f32_16x16x32_bf16 v[68:71], v[172:175], v[214:217], v[68:71]
	v_mfma_f32_16x16x32_bf16 v[64:67], v[180:183], v[214:217], v[64:67]
	s_setprio 0
	s_barrier
	s_add_i32 s66, s53, s81
	v_lshl_add_u64 v[144:145], s[4:5], 0, v[130:131]
	s_mov_b32 m0, s66
	ds_read_b128 v[184:187], v151 offset:16384
	ds_read_b128 v[188:191], v151 offset:17408
	ds_read_b128 v[192:195], v151 offset:18432
	ds_read_b128 v[196:199], v151 offset:19456
	ds_read_b128 v[200:203], v151 offset:20480
	ds_read_b128 v[204:207], v151 offset:21504
	ds_read_b128 v[210:213], v151 offset:22528
	ds_read_b128 v[214:217], v151 offset:23552
	global_load_lds_dwordx4 v[144:145], off
	s_add_i32 m0, s66, 0x2000
	s_add_u32 s66, s4, 0x40000
	v_lshl_add_u64 v[218:219], s[4:5], 0, v[134:135]
	s_addc_u32 s67, s5, 0
	s_add_i32 s68, s54, s81
	global_load_lds_dwordx4 v[218:219], off
	v_lshl_add_u64 v[220:221], s[66:67], 0, v[130:131]
	s_mov_b32 m0, s68
	v_lshl_add_u64 v[222:223], s[46:47], 0, v[132:133]
	global_load_lds_dwordx4 v[220:221], off
	v_lshl_add_u64 v[220:221], s[66:67], 0, v[134:135]
	s_add_i32 m0, s68, 0x2000
	s_nop 0
	global_load_lds_dwordx4 v[220:221], off
	v_lshl_add_u64 v[220:221], s[46:47], 0, v[128:129]
	s_mov_b32 m0, s33
	s_nop 0
	global_load_lds_dwordx4 v[220:221], off
	s_mov_b32 m0, s35
	s_nop 0
	global_load_lds_dwordx4 v[222:223], off
	s_waitcnt vmcnt(8) lgkmcnt(0)
	s_setprio 1
	s_barrier
; #define PG8_STAGE(bufoff, gbase, voff) do { _Pragma("unroll") for (int _i = 0; _i < 2; ++_i) \
;         __builtin_amdgcn_global_load_lds((const unsigned*)((const char*)(gbase) + (voff)[_i]), (LAS unsigned*)(lds + (bufoff) + ldsw + _i * 8192), 16, 0, 0); } while (0)
; #define PG8_LDA(dst, b, h) do { _Pragma("unroll") for (int m = 0; m < 4; ++m) _Pragma("unroll") for (int k = 0; k < 2; ++k) dst[m][k] = *(const LAS bf16x8*)(lds + PG8_SA(b, h) + aoff + m * 2048 + k * 1024); } while (0)
; #define PG8_LDB(dst, b, h) do { _Pragma("unroll") for (int n = 0; n < 2; ++n) _Pragma("unroll") for (int k = 0; k < 2; ++k) dst[n][k] = *(const LAS bf16x8*)(lds + PG8_SB(b, h) + boff + n * 2048 + k * 1024); } while (0)
; #define PG8_MMA(ai, bj, At, Bt) do { __builtin_amdgcn_s_setprio(1); _Pragma("unroll") for (int m = 0; m < 4; ++m) _Pragma("unroll") for (int n = 0; n < 2; ++n) _Pragma("unroll") for (int k = 0; k < 2; ++k) \
;         acc[ai][bj][m][n] = __builtin_amdgcn_mfma_f32_16x16x32_bf16(Bt[n][k], At[m][k], acc[ai][bj][m][n], 0, 0, 0); __builtin_amdgcn_s_setprio(0); } while (0)
; #define PG8_WAIT_V(n) asm volatile("s_waitcnt vmcnt(" #n ")" ::: "memory")
; #define PG8_WAIT_L(n) asm volatile("s_waitcnt lgkmcnt(" #n ")" ::: "memory")
; #define PG8_BAR __builtin_amdgcn_s_barrier()
; #define PG8_SCHED __builtin_amdgcn_sched_barrier(0)
; template <class Epi, class Sched>
; __device__ __forceinline__ void gemm_phase(LAS unsigned char* lds, const Gemm g, const Sched& S, const Epi& E, const int wave_s) {
;     ...
;             PG8_WAIT_V(8); PG8_WAIT_L(0); PG8_BAR; PG8_MMA(1, 0, At, B0); PG8_MMA(1, 1, At, B1); PG8_BAR; PG8_SCHED;
;             PG8_LDB(B0, 1, 0); PG8_LDB(B1, 1, 1); PG8_SCHED; PG8_LDA(At, 1, 0); PG8_STAGE(PG8_SA(0, 1), a2 + hstepA, voffA);
;             PG8_WAIT_V(8); PG8_WAIT_L(0); PG8_BAR; PG8_MMA(0, 0, At, B0); PG8_MMA(0, 1, At, B1); PG8_BAR; PG8_SCHED;
	v_mfma_f32_16x16x32_bf16 v[60:63], v[152:155], v[184:187], v[60:63]
	v_mfma_f32_16x16x32_bf16 v[56:59], v[160:163], v[184:187], v[56:59]
	v_mfma_f32_16x16x32_bf16 v[52:55], v[152:155], v[192:195], v[52:55]
	v_mfma_f32_16x16x32_bf16 v[44:47], v[160:163], v[192:195], v[44:47]
	v_mfma_f32_16x16x32_bf16 v[36:39], v[152:155], v[200:203], v[36:39]
	v_mfma_f32_16x16x32_bf16 v[28:31], v[160:163], v[200:203], v[28:31]
	v_mfma_f32_16x16x32_bf16 v[20:23], v[152:155], v[210:213], v[20:23]
	v_mfma_f32_16x16x32_bf16 v[12:15], v[160:163], v[210:213], v[12:15]
	v_mfma_f32_16x16x32_bf16 v[60:63], v[156:159], v[188:191], v[60:63]
	v_mfma_f32_16x16x32_bf16 v[56:59], v[164:167], v[188:191], v[56:59]
	v_mfma_f32_16x16x32_bf16 v[52:55], v[156:159], v[196:199], v[52:55]
	v_mfma_f32_16x16x32_bf16 v[44:47], v[164:167], v[196:199], v[44:47]
	v_mfma_f32_16x16x32_bf16 v[36:39], v[156:159], v[204:207], v[36:39]
	v_mfma_f32_16x16x32_bf16 v[28:31], v[164:167], v[204:207], v[28:31]
	v_mfma_f32_16x16x32_bf16 v[20:23], v[156:159], v[214:217], v[20:23]
	v_mfma_f32_16x16x32_bf16 v[12:15], v[164:167], v[214:217], v[12:15]
	s_setprio 0
	s_setprio 1
	v_mfma_f32_16x16x32_bf16 v[48:51], v[168:171], v[184:187], v[48:51]
	v_mfma_f32_16x16x32_bf16 v[40:43], v[176:179], v[184:187], v[40:43]
	v_mfma_f32_16x16x32_bf16 v[32:35], v[168:171], v[192:195], v[32:35]
	v_mfma_f32_16x16x32_bf16 v[24:27], v[176:179], v[192:195], v[24:27]
	v_mfma_f32_16x16x32_bf16 v[16:19], v[168:171], v[200:203], v[16:19]
	v_mfma_f32_16x16x32_bf16 v[8:11], v[176:179], v[200:203], v[8:11]
	v_mfma_f32_16x16x32_bf16 v[4:7], v[168:171], v[210:213], v[4:7]
	v_mfma_f32_16x16x32_bf16 v[0:3], v[176:179], v[210:213], v[0:3]
	v_mfma_f32_16x16x32_bf16 v[48:51], v[172:175], v[188:191], v[48:51]
	v_mfma_f32_16x16x32_bf16 v[40:43], v[180:183], v[188:191], v[40:43]
	v_mfma_f32_16x16x32_bf16 v[32:35], v[172:175], v[196:199], v[32:35]
	v_mfma_f32_16x16x32_bf16 v[24:27], v[180:183], v[196:199], v[24:27]
	v_mfma_f32_16x16x32_bf16 v[16:19], v[172:175], v[204:207], v[16:19]
	v_mfma_f32_16x16x32_bf16 v[8:11], v[180:183], v[204:207], v[8:11]
	v_mfma_f32_16x16x32_bf16 v[4:7], v[172:175], v[214:217], v[4:7]
	v_mfma_f32_16x16x32_bf16 v[0:3], v[180:183], v[214:217], v[0:3]
	s_setprio 0
	s_barrier
	s_add_i32 s66, 0, 0x18000
	s_add_i32 s67, 0, 0x1c000
	v_add_u32_e32 v164, s66, v147
	v_add_u32_e32 v180, s67, v147
	ds_read_b128 v[152:155], v164
	ds_read_b128 v[156:159], v164 offset:1024
	ds_read_b128 v[160:163], v164 offset:2048
	ds_read_b128 v[164:167], v164 offset:3072
	ds_read_b128 v[168:171], v180
	ds_read_b128 v[172:175], v180 offset:1024
	ds_read_b128 v[176:179], v180 offset:2048
	ds_read_b128 v[180:183], v180 offset:3072
	s_add_u32 s46, s46, 0x40000
	s_addc_u32 s47, s47, 0
	s_mov_b32 m0, s37
	v_lshl_add_u64 v[224:225], s[46:47], 0, v[128:129]
	ds_read_b128 v[184:187], v151 offset:32768
	ds_read_b128 v[188:191], v151 offset:33792
	ds_read_b128 v[192:195], v151 offset:34816
	ds_read_b128 v[196:199], v151 offset:35840
	ds_read_b128 v[200:203], v151 offset:36864
	ds_read_b128 v[204:207], v151 offset:37888
	ds_read_b128 v[210:213], v151 offset:38912
	ds_read_b128 v[214:217], v151 offset:39936
	global_load_lds_dwordx4 v[224:225], off
	v_lshl_add_u64 v[224:225], s[46:47], 0, v[132:133]
	s_mov_b32 m0, s43
	s_nop 0
	global_load_lds_dwordx4 v[224:225], off
	s_waitcnt vmcnt(8) lgkmcnt(0)
	s_setprio 1
	s_barrier
	v_mfma_f32_16x16x32_bf16 v[124:127], v[152:155], v[184:187], v[124:127]
	v_mfma_f32_16x16x32_bf16 v[120:123], v[160:163], v[184:187], v[120:123]
	v_mfma_f32_16x16x32_bf16 v[116:119], v[152:155], v[192:195], v[116:119]
	v_mfma_f32_16x16x32_bf16 v[108:111], v[160:163], v[192:195], v[108:111]
	v_mfma_f32_16x16x32_bf16 v[100:103], v[152:155], v[200:203], v[100:103]
	v_mfma_f32_16x16x32_bf16 v[92:95], v[160:163], v[200:203], v[92:95]
	v_mfma_f32_16x16x32_bf16 v[84:87], v[152:155], v[210:213], v[84:87]
	v_mfma_f32_16x16x32_bf16 v[76:79], v[160:163], v[210:213], v[76:79]
	v_mfma_f32_16x16x32_bf16 v[124:127], v[156:159], v[188:191], v[124:127]
	v_mfma_f32_16x16x32_bf16 v[120:123], v[164:167], v[188:191], v[120:123]
	v_mfma_f32_16x16x32_bf16 v[116:119], v[156:159], v[196:199], v[116:119]
	v_mfma_f32_16x16x32_bf16 v[108:111], v[164:167], v[196:199], v[108:111]
	v_mfma_f32_16x16x32_bf16 v[100:103], v[156:159], v[204:207], v[100:103]
	v_mfma_f32_16x16x32_bf16 v[92:95], v[164:167], v[204:207], v[92:95]
	v_mfma_f32_16x16x32_bf16 v[84:87], v[156:159], v[214:217], v[84:87]
	v_mfma_f32_16x16x32_bf16 v[76:79], v[164:167], v[214:217], v[76:79]
	s_setprio 0
	s_setprio 1
	v_mfma_f32_16x16x32_bf16 v[112:115], v[168:171], v[184:187], v[112:115]
	v_mfma_f32_16x16x32_bf16 v[104:107], v[176:179], v[184:187], v[104:107]
	v_mfma_f32_16x16x32_bf16 v[96:99], v[168:171], v[192:195], v[96:99]
	v_mfma_f32_16x16x32_bf16 v[88:91], v[176:179], v[192:195], v[88:91]
	v_mfma_f32_16x16x32_bf16 v[80:83], v[168:171], v[200:203], v[80:83]
	v_mfma_f32_16x16x32_bf16 v[72:75], v[176:179], v[200:203], v[72:75]
	v_mfma_f32_16x16x32_bf16 v[68:71], v[168:171], v[210:213], v[68:71]
	v_mfma_f32_16x16x32_bf16 v[64:67], v[176:179], v[210:213], v[64:67]
	v_mfma_f32_16x16x32_bf16 v[112:115], v[172:175], v[188:191], v[112:115]
	v_mfma_f32_16x16x32_bf16 v[104:107], v[180:183], v[188:191], v[104:107]
	v_mfma_f32_16x16x32_bf16 v[96:99], v[172:175], v[196:199], v[96:99]
	v_mfma_f32_16x16x32_bf16 v[88:91], v[180:183], v[196:199], v[88:91]
	v_mfma_f32_16x16x32_bf16 v[80:83], v[172:175], v[204:207], v[80:83]
	v_mfma_f32_16x16x32_bf16 v[72:75], v[180:183], v[204:207], v[72:75]
	v_mfma_f32_16x16x32_bf16 v[68:71], v[172:175], v[214:217], v[68:71]
	v_mfma_f32_16x16x32_bf16 v[64:67], v[180:183], v[214:217], v[64:67]
	s_setprio 0
	s_barrier
; #define PG8_STAGE(bufoff, gbase, voff) do { _Pragma("unroll") for (int _i = 0; _i < 2; ++_i) \
;         __builtin_amdgcn_global_load_lds((const unsigned*)((const char*)(gbase) + (voff)[_i]), (LAS unsigned*)(lds + (bufoff) + ldsw + _i * 8192), 16, 0, 0); } while (0)
; #define PG8_LDA(dst, b, h) do { _Pragma("unroll") for (int m = 0; m < 4; ++m) _Pragma("unroll") for (int k = 0; k < 2; ++k) dst[m][k] = *(const LAS bf16x8*)(lds + PG8_SA(b, h) + aoff + m * 2048 + k * 1024); } while (0)
; #define PG8_MMA(ai, bj, At, Bt) do { __builtin_amdgcn_s_setprio(1); _Pragma("unroll") for (int m = 0; m < 4; ++m) _Pragma("unroll") for (int n = 0; n < 2; ++n) _Pragma("unroll") for (int k = 0; k < 2; ++k) \
;         acc[ai][bj][m][n] = __builtin_amdgcn_mfma_f32_16x16x32_bf16(Bt[n][k], At[m][k], acc[ai][bj][m][n], 0, 0, 0); __builtin_amdgcn_s_setprio(0); } while (0)
; #define PG8_WAIT_V(n) asm volatile("s_waitcnt vmcnt(" #n ")" ::: "memory")
; #define PG8_WAIT_L(n) asm volatile("s_waitcnt lgkmcnt(" #n ")" ::: "memory")
; #define PG8_BAR __builtin_amdgcn_s_barrier()
; #define PG8_SCHED __builtin_amdgcn_sched_barrier(0)
; template <class Epi, class Sched>
; __device__ __forceinline__ void gemm_phase(LAS unsigned char* lds, const Gemm g, const Sched& S, const Epi& E, const int wave_s) {
;     ...
;             PG8_LDA(At, 1, 1); PG8_STAGE(PG8_SB(1, 0), b3, voffB); PG8_STAGE(PG8_SB(1, 1), b3 + hstepB, voffB); PG8_STAGE(PG8_SA(1, 0), a3, voffA);
;             PG8_WAIT_V(8); PG8_WAIT_L(0); PG8_BAR; PG8_MMA(1, 0, At, B0); PG8_MMA(1, 1, At, B1); PG8_BAR; PG8_SCHED;
;         }
	s_add_i32 s46, s66, s81
	v_lshl_add_u64 v[144:145], v[144:145], 0, s[14:15]
	s_mov_b32 m0, s46
	ds_read_b128 v[184:187], v151 offset:49152
	ds_read_b128 v[188:191], v151 offset:50176
	ds_read_b128 v[192:195], v151 offset:51200
	ds_read_b128 v[196:199], v151 offset:52224
	ds_read_b128 v[200:203], v151 offset:53248
	ds_read_b128 v[204:207], v151 offset:54272
	ds_read_b128 v[210:213], v151 offset:55296
	ds_read_b128 v[214:217], v151 offset:56320
	global_load_lds_dwordx4 v[144:145], off
	s_add_i32 m0, s46, 0x2000
	s_add_u32 s4, s4, 0x40080
	v_lshl_add_u64 v[144:145], v[218:219], 0, s[14:15]
	s_addc_u32 s5, s5, 0
	s_add_i32 s46, s67, s81
	global_load_lds_dwordx4 v[144:145], off
	v_lshl_add_u64 v[144:145], s[4:5], 0, v[130:131]
	s_mov_b32 m0, s46
	s_nop 0
	global_load_lds_dwordx4 v[144:145], off
	v_lshl_add_u64 v[144:145], s[4:5], 0, v[134:135]
	s_add_i32 m0, s46, 0x2000
	s_nop 0
	global_load_lds_dwordx4 v[144:145], off
	v_lshl_add_u64 v[144:145], v[220:221], 0, s[14:15]
	s_mov_b32 m0, s49
	s_nop 0
	global_load_lds_dwordx4 v[144:145], off
	v_lshl_add_u64 v[144:145], v[222:223], 0, s[14:15]
	s_mov_b32 m0, s50
	s_nop 0
	global_load_lds_dwordx4 v[144:145], off
	s_waitcnt vmcnt(8) lgkmcnt(0)
	s_setprio 1
	s_barrier
	v_mfma_f32_16x16x32_bf16 v[60:63], v[152:155], v[184:187], v[60:63]
	v_mfma_f32_16x16x32_bf16 v[56:59], v[160:163], v[184:187], v[56:59]
	v_mfma_f32_16x16x32_bf16 v[52:55], v[152:155], v[192:195], v[52:55]
	v_mfma_f32_16x16x32_bf16 v[44:47], v[160:163], v[192:195], v[44:47]
	v_mfma_f32_16x16x32_bf16 v[36:39], v[152:155], v[200:203], v[36:39]
	v_mfma_f32_16x16x32_bf16 v[28:31], v[160:163], v[200:203], v[28:31]
	v_mfma_f32_16x16x32_bf16 v[20:23], v[152:155], v[210:213], v[20:23]
	v_mfma_f32_16x16x32_bf16 v[12:15], v[160:163], v[210:213], v[12:15]
	v_mfma_f32_16x16x32_bf16 v[60:63], v[156:159], v[188:191], v[60:63]
	v_mfma_f32_16x16x32_bf16 v[56:59], v[164:167], v[188:191], v[56:59]
	v_mfma_f32_16x16x32_bf16 v[52:55], v[156:159], v[196:199], v[52:55]
	v_mfma_f32_16x16x32_bf16 v[44:47], v[164:167], v[196:199], v[44:47]
	v_mfma_f32_16x16x32_bf16 v[36:39], v[156:159], v[204:207], v[36:39]
	v_mfma_f32_16x16x32_bf16 v[28:31], v[164:167], v[204:207], v[28:31]
	v_mfma_f32_16x16x32_bf16 v[20:23], v[156:159], v[214:217], v[20:23]
	v_mfma_f32_16x16x32_bf16 v[12:15], v[164:167], v[214:217], v[12:15]
	s_setprio 0
	s_setprio 1
	v_mfma_f32_16x16x32_bf16 v[48:51], v[168:171], v[184:187], v[48:51]
	v_mfma_f32_16x16x32_bf16 v[40:43], v[176:179], v[184:187], v[40:43]
	v_mfma_f32_16x16x32_bf16 v[32:35], v[168:171], v[192:195], v[32:35]
	v_mfma_f32_16x16x32_bf16 v[24:27], v[176:179], v[192:195], v[24:27]
	v_mfma_f32_16x16x32_bf16 v[16:19], v[168:171], v[200:203], v[16:19]
	v_mfma_f32_16x16x32_bf16 v[8:11], v[176:179], v[200:203], v[8:11]
	v_mfma_f32_16x16x32_bf16 v[4:7], v[168:171], v[210:213], v[4:7]
	v_mfma_f32_16x16x32_bf16 v[0:3], v[176:179], v[210:213], v[0:3]
	v_mfma_f32_16x16x32_bf16 v[48:51], v[172:175], v[188:191], v[48:51]
	v_mfma_f32_16x16x32_bf16 v[40:43], v[180:183], v[188:191], v[40:43]
	v_mfma_f32_16x16x32_bf16 v[32:35], v[172:175], v[196:199], v[32:35]
	v_mfma_f32_16x16x32_bf16 v[24:27], v[180:183], v[196:199], v[24:27]
	v_mfma_f32_16x16x32_bf16 v[16:19], v[172:175], v[204:207], v[16:19]
	v_mfma_f32_16x16x32_bf16 v[8:11], v[180:183], v[204:207], v[8:11]
	v_mfma_f32_16x16x32_bf16 v[4:7], v[172:175], v[214:217], v[4:7]
	v_mfma_f32_16x16x32_bf16 v[0:3], v[180:183], v[214:217], v[0:3]
	s_setprio 0
	s_barrier
	s_add_i32 s65, s65, 2
	s_add_u32 s44, s44, 0x100
	s_addc_u32 s45, s45, 0
	s_add_u32 s63, s63, 0x100
	s_addc_u32 s64, s64, 0
	s_cmp_gt_u32 s65, 13
	s_cbranch_scc0 .LBB0_125
	s_and_b64 vcc, exec, s[16:17]
	s_cbranch_vccz .LBB0_128
	s_barrier

; #define PG8_STAGE(bufoff, gbase, voff) do { _Pragma("unroll") for (int _i = 0; _i < 2; ++_i) \
;         __builtin_amdgcn_global_load_lds((const unsigned*)((const char*)(gbase) + (voff)[_i]), (LAS unsigned*)(lds + (bufoff) + ldsw + _i * 8192), 16, 0, 0); } while (0)
; #define PG8_LDA(dst, b, h) do { _Pragma("unroll") for (int m = 0; m < 4; ++m) _Pragma("unroll") for (int k = 0; k < 2; ++k) dst[m][k] = *(const LAS bf16x8*)(lds + PG8_SA(b, h) + aoff + m * 2048 + k * 1024); } while (0)
; #define PG8_LDB(dst, b, h) do { _Pragma("unroll") for (int n = 0; n < 2; ++n) _Pragma("unroll") for (int k = 0; k < 2; ++k) dst[n][k] = *(const LAS bf16x8*)(lds + PG8_SB(b, h) + boff + n * 2048 + k * 1024); } while (0)
; #define PG8_MMA(ai, bj, At, Bt) do { __builtin_amdgcn_s_setprio(1); _Pragma("unroll") for (int m = 0; m < 4; ++m) _Pragma("unroll") for (int n = 0; n < 2; ++n) _Pragma("unroll") for (int k = 0; k < 2; ++k) \
;         acc[ai][bj][m][n] = __builtin_amdgcn_mfma_f32_16x16x32_bf16(Bt[n][k], At[m][k], acc[ai][bj][m][n], 0, 0, 0); __builtin_amdgcn_s_setprio(0); } while (0)
; #define PG8_WAIT_V(n) asm volatile("s_waitcnt vmcnt(" #n ")" ::: "memory")
; #define PG8_WAIT_L(n) asm volatile("s_waitcnt lgkmcnt(" #n ")" ::: "memory")
; #define PG8_BAR __builtin_amdgcn_s_barrier()
; #define PG8_SCHED __builtin_amdgcn_sched_barrier(0)
; template <class Epi, class Sched>
; __device__ __forceinline__ void gemm_phase(LAS unsigned char* lds, const Gemm g, const Sched& S, const Epi& E, const int wave_s) {
;     ...
;             const bool last = (t == nt - 2);
;             const char* a1 = cA + (size_t)(t + 1) * kstep;
;             const char* a2 = last ? nA : cA + (size_t)(t + 2) * kstep; const char* b2 = last ? nB : cB + (size_t)(t + 2) * kstep;
;             const char* a3 = a2 + kstep; const char* b3 = b2 + kstep;
;             PG8_LDB(B0, 0, 0); PG8_LDB(B1, 0, 1); PG8_SCHED; PG8_LDA(At, 0, 0); PG8_STAGE(PG8_SA(1, 1), a1 + hstepA, voffA);
;             PG8_WAIT_V(8); PG8_WAIT_L(0); PG8_BAR; PG8_MMA(0, 0, At, B0); PG8_MMA(0, 1, At, B1); PG8_BAR; PG8_SCHED;
;             PG8_LDA(At, 0, 1); PG8_STAGE(PG8_SB(0, 0), b2, voffB); PG8_STAGE(PG8_SB(0, 1), b2 + hstepB, voffB); PG8_STAGE(PG8_SA(0, 0), a2, voffA);
;             PG8_WAIT_V(8); PG8_WAIT_L(0); PG8_BAR; PG8_MMA(1, 0, At, B0); PG8_MMA(1, 1, At, B1); PG8_BAR; PG8_SCHED;
.LBB0_194:
	ds_read_b128 v[144:147], v151
	ds_read_b128 v[154:157], v151 offset:1024
	ds_read_b128 v[158:161], v151 offset:2048
	ds_read_b128 v[162:165], v151 offset:3072
	ds_read_b128 v[166:169], v152
	ds_read_b128 v[170:173], v152 offset:1024
	ds_read_b128 v[174:177], v152 offset:2048
	ds_read_b128 v[178:181], v152 offset:3072
	s_add_u32 s4, s24, 0xfffc0080
	s_addc_u32 s5, s25, -1
	s_cmp_eq_u32 s54, 12
	s_cselect_b32 s27, s19, s5
	s_cselect_b32 s26, s50, s4
	s_cselect_b32 s5, s17, s53
	s_cselect_b32 s4, s51, s52
	v_lshl_add_u64 v[206:207], s[24:25], 0, v[136:137]
	s_add_i32 m0, s30, 0xc000
	ds_read_b128 v[182:185], v153
	ds_read_b128 v[186:189], v153 offset:1024
	ds_read_b128 v[190:193], v153 offset:2048
	ds_read_b128 v[194:197], v153 offset:3072
	ds_read_b128 v[198:201], v153 offset:4096
	ds_read_b128 v[202:205], v153 offset:5120
	ds_read_b128 v[210:213], v153 offset:6144
	ds_read_b128 v[214:217], v153 offset:7168
	global_load_lds_dwordx4 v[206:207], off
	v_lshl_add_u64 v[206:207], s[24:25], 0, v[138:139]
	s_add_i32 m0, s30, 0xe000
	s_nop 0
	global_load_lds_dwordx4 v[206:207], off
	s_waitcnt vmcnt(8) lgkmcnt(0)
	s_setprio 1
	s_barrier
	v_mfma_f32_16x16x32_bf16 v[124:127], v[144:147], v[182:185], v[124:127]
	v_mfma_f32_16x16x32_bf16 v[120:123], v[158:161], v[182:185], v[120:123]
	v_mfma_f32_16x16x32_bf16 v[116:119], v[144:147], v[190:193], v[116:119]
	v_mfma_f32_16x16x32_bf16 v[108:111], v[158:161], v[190:193], v[108:111]
	v_mfma_f32_16x16x32_bf16 v[100:103], v[144:147], v[198:201], v[100:103]
	v_mfma_f32_16x16x32_bf16 v[92:95], v[158:161], v[198:201], v[92:95]
	v_mfma_f32_16x16x32_bf16 v[84:87], v[144:147], v[210:213], v[84:87]
	v_mfma_f32_16x16x32_bf16 v[76:79], v[158:161], v[210:213], v[76:79]
	v_mfma_f32_16x16x32_bf16 v[124:127], v[154:157], v[186:189], v[124:127]
	v_mfma_f32_16x16x32_bf16 v[120:123], v[162:165], v[186:189], v[120:123]
	v_mfma_f32_16x16x32_bf16 v[116:119], v[154:157], v[194:197], v[116:119]
	v_mfma_f32_16x16x32_bf16 v[108:111], v[162:165], v[194:197], v[108:111]
	v_mfma_f32_16x16x32_bf16 v[100:103], v[154:157], v[202:205], v[100:103]
	v_mfma_f32_16x16x32_bf16 v[92:95], v[162:165], v[202:205], v[92:95]
	v_mfma_f32_16x16x32_bf16 v[84:87], v[154:157], v[214:217], v[84:87]
	v_mfma_f32_16x16x32_bf16 v[76:79], v[162:165], v[214:217], v[76:79]
	s_setprio 0
	s_setprio 1
	v_mfma_f32_16x16x32_bf16 v[112:115], v[166:169], v[182:185], v[112:115]
	v_mfma_f32_16x16x32_bf16 v[104:107], v[174:177], v[182:185], v[104:107]
	v_mfma_f32_16x16x32_bf16 v[96:99], v[166:169], v[190:193], v[96:99]
	v_mfma_f32_16x16x32_bf16 v[88:91], v[174:177], v[190:193], v[88:91]
	v_mfma_f32_16x16x32_bf16 v[80:83], v[166:169], v[198:201], v[80:83]
	v_mfma_f32_16x16x32_bf16 v[72:75], v[174:177], v[198:201], v[72:75]
	v_mfma_f32_16x16x32_bf16 v[68:71], v[166:169], v[210:213], v[68:71]
	v_mfma_f32_16x16x32_bf16 v[64:67], v[174:177], v[210:213], v[64:67]
	v_mfma_f32_16x16x32_bf16 v[112:115], v[170:173], v[186:189], v[112:115]
	v_mfma_f32_16x16x32_bf16 v[104:107], v[178:181], v[186:189], v[104:107]
	v_mfma_f32_16x16x32_bf16 v[96:99], v[170:173], v[194:197], v[96:99]
	v_mfma_f32_16x16x32_bf16 v[88:91], v[178:181], v[194:197], v[88:91]
	v_mfma_f32_16x16x32_bf16 v[80:83], v[170:173], v[202:205], v[80:83]
	v_mfma_f32_16x16x32_bf16 v[72:75], v[178:181], v[202:205], v[72:75]
	v_mfma_f32_16x16x32_bf16 v[68:71], v[170:173], v[214:217], v[68:71]
	v_mfma_f32_16x16x32_bf16 v[64:67], v[178:181], v[214:217], v[64:67]
	s_setprio 0
	s_barrier
	s_add_i32 s55, s45, s81
	v_lshl_add_u64 v[206:207], s[4:5], 0, v[132:133]
	s_mov_b32 m0, s55
	ds_read_b128 v[182:185], v153 offset:16384
	ds_read_b128 v[186:189], v153 offset:17408
	ds_read_b128 v[190:193], v153 offset:18432
	ds_read_b128 v[194:197], v153 offset:19456
	ds_read_b128 v[198:201], v153 offset:20480
	ds_read_b128 v[202:205], v153 offset:21504
	ds_read_b128 v[210:213], v153 offset:22528
	ds_read_b128 v[214:217], v153 offset:23552
	global_load_lds_dwordx4 v[206:207], off
	s_add_i32 m0, s55, 0x2000
	s_add_u32 s58, s4, 0x40000
	v_lshl_add_u64 v[218:219], s[4:5], 0, v[128:129]
	s_addc_u32 s59, s5, 0
	s_add_i32 s55, s46, s81
	global_load_lds_dwordx4 v[218:219], off
	v_lshl_add_u64 v[220:221], s[58:59], 0, v[132:133]
	s_mov_b32 m0, s55
	v_lshl_add_u64 v[222:223], s[26:27], 0, v[130:131]
	global_load_lds_dwordx4 v[220:221], off
	v_lshl_add_u64 v[220:221], s[58:59], 0, v[128:129]
	s_add_i32 m0, s55, 0x2000
	s_nop 0
	global_load_lds_dwordx4 v[220:221], off
	v_lshl_add_u64 v[220:221], s[26:27], 0, v[134:135]
	s_mov_b32 m0, s30
	s_nop 0
	global_load_lds_dwordx4 v[220:221], off
	s_mov_b32 m0, s31
	s_nop 0
	global_load_lds_dwordx4 v[222:223], off
	s_waitcnt vmcnt(8) lgkmcnt(0)
	s_setprio 1
	s_barrier
; #define PG8_STAGE(bufoff, gbase, voff) do { _Pragma("unroll") for (int _i = 0; _i < 2; ++_i) \
;         __builtin_amdgcn_global_load_lds((const unsigned*)((const char*)(gbase) + (voff)[_i]), (LAS unsigned*)(lds + (bufoff) + ldsw + _i * 8192), 16, 0, 0); } while (0)
; #define PG8_LDA(dst, b, h) do { _Pragma("unroll") for (int m = 0; m < 4; ++m) _Pragma("unroll") for (int k = 0; k < 2; ++k) dst[m][k] = *(const LAS bf16x8*)(lds + PG8_SA(b, h) + aoff + m * 2048 + k * 1024); } while (0)
; #define PG8_LDB(dst, b, h) do { _Pragma("unroll") for (int n = 0; n < 2; ++n) _Pragma("unroll") for (int k = 0; k < 2; ++k) dst[n][k] = *(const LAS bf16x8*)(lds + PG8_SB(b, h) + boff + n * 2048 + k * 1024); } while (0)
; #define PG8_MMA(ai, bj, At, Bt) do { __builtin_amdgcn_s_setprio(1); _Pragma("unroll") for (int m = 0; m < 4; ++m) _Pragma("unroll") for (int n = 0; n < 2; ++n) _Pragma("unroll") for (int k = 0; k < 2; ++k) \
;         acc[ai][bj][m][n] = __builtin_amdgcn_mfma_f32_16x16x32_bf16(Bt[n][k], At[m][k], acc[ai][bj][m][n], 0, 0, 0); __builtin_amdgcn_s_setprio(0); } while (0)
; #define PG8_WAIT_V(n) asm volatile("s_waitcnt vmcnt(" #n ")" ::: "memory")
; #define PG8_WAIT_L(n) asm volatile("s_waitcnt lgkmcnt(" #n ")" ::: "memory")
; #define PG8_BAR __builtin_amdgcn_s_barrier()
; #define PG8_SCHED __builtin_amdgcn_sched_barrier(0)
; template <class Epi, class Sched>
; __device__ __forceinline__ void gemm_phase(LAS unsigned char* lds, const Gemm g, const Sched& S, const Epi& E, const int wave_s) {
;     ...
;             PG8_LDA(At, 0, 1); PG8_STAGE(PG8_SB(0, 0), b2, voffB); PG8_STAGE(PG8_SB(0, 1), b2 + hstepB, voffB); PG8_STAGE(PG8_SA(0, 0), a2, voffA);
;             PG8_WAIT_V(8); PG8_WAIT_L(0); PG8_BAR; PG8_MMA(1, 0, At, B0); PG8_MMA(1, 1, At, B1); PG8_BAR; PG8_SCHED;
;             PG8_LDB(B0, 1, 0); PG8_LDB(B1, 1, 1); PG8_SCHED; PG8_LDA(At, 1, 0); PG8_STAGE(PG8_SA(0, 1), a2 + hstepA, voffA);
;             PG8_WAIT_V(8); PG8_WAIT_L(0); PG8_BAR; PG8_MMA(0, 0, At, B0); PG8_MMA(0, 1, At, B1); PG8_BAR; PG8_SCHED;
	v_mfma_f32_16x16x32_bf16 v[60:63], v[144:147], v[182:185], v[60:63]
	v_mfma_f32_16x16x32_bf16 v[56:59], v[158:161], v[182:185], v[56:59]
	v_mfma_f32_16x16x32_bf16 v[52:55], v[144:147], v[190:193], v[52:55]
	v_mfma_f32_16x16x32_bf16 v[44:47], v[158:161], v[190:193], v[44:47]
	v_mfma_f32_16x16x32_bf16 v[36:39], v[144:147], v[198:201], v[36:39]
	v_mfma_f32_16x16x32_bf16 v[28:31], v[158:161], v[198:201], v[28:31]
	v_mfma_f32_16x16x32_bf16 v[20:23], v[144:147], v[210:213], v[20:23]
	v_mfma_f32_16x16x32_bf16 v[12:15], v[158:161], v[210:213], v[12:15]
	v_mfma_f32_16x16x32_bf16 v[60:63], v[154:157], v[186:189], v[60:63]
	v_mfma_f32_16x16x32_bf16 v[56:59], v[162:165], v[186:189], v[56:59]
	v_mfma_f32_16x16x32_bf16 v[52:55], v[154:157], v[194:197], v[52:55]
	v_mfma_f32_16x16x32_bf16 v[44:47], v[162:165], v[194:197], v[44:47]
	v_mfma_f32_16x16x32_bf16 v[36:39], v[154:157], v[202:205], v[36:39]
	v_mfma_f32_16x16x32_bf16 v[28:31], v[162:165], v[202:205], v[28:31]
	v_mfma_f32_16x16x32_bf16 v[20:23], v[154:157], v[214:217], v[20:23]
	v_mfma_f32_16x16x32_bf16 v[12:15], v[162:165], v[214:217], v[12:15]
	s_setprio 0
	s_setprio 1
	v_mfma_f32_16x16x32_bf16 v[48:51], v[166:169], v[182:185], v[48:51]
	v_mfma_f32_16x16x32_bf16 v[40:43], v[174:177], v[182:185], v[40:43]
	v_mfma_f32_16x16x32_bf16 v[32:35], v[166:169], v[190:193], v[32:35]
	v_mfma_f32_16x16x32_bf16 v[24:27], v[174:177], v[190:193], v[24:27]
	v_mfma_f32_16x16x32_bf16 v[16:19], v[166:169], v[198:201], v[16:19]
	v_mfma_f32_16x16x32_bf16 v[8:11], v[174:177], v[198:201], v[8:11]
	v_mfma_f32_16x16x32_bf16 v[4:7], v[166:169], v[210:213], v[4:7]
	v_mfma_f32_16x16x32_bf16 v[0:3], v[174:177], v[210:213], v[0:3]
	v_mfma_f32_16x16x32_bf16 v[48:51], v[170:173], v[186:189], v[48:51]
	v_mfma_f32_16x16x32_bf16 v[40:43], v[178:181], v[186:189], v[40:43]
	v_mfma_f32_16x16x32_bf16 v[32:35], v[170:173], v[194:197], v[32:35]
	v_mfma_f32_16x16x32_bf16 v[24:27], v[178:181], v[194:197], v[24:27]
	v_mfma_f32_16x16x32_bf16 v[16:19], v[170:173], v[202:205], v[16:19]
	v_mfma_f32_16x16x32_bf16 v[8:11], v[178:181], v[202:205], v[8:11]
	v_mfma_f32_16x16x32_bf16 v[4:7], v[170:173], v[214:217], v[4:7]
	v_mfma_f32_16x16x32_bf16 v[0:3], v[178:181], v[214:217], v[0:3]
	s_setprio 0
	s_barrier
	s_add_i32 s55, 0, 0x18000
	s_add_i32 s57, 0, 0x1c000
	v_add_u32_e32 v162, s55, v149
	v_add_u32_e32 v178, s57, v149
	ds_read_b128 v[144:147], v162
	ds_read_b128 v[154:157], v162 offset:1024
	ds_read_b128 v[158:161], v162 offset:2048
	ds_read_b128 v[162:165], v162 offset:3072
	ds_read_b128 v[166:169], v178
	ds_read_b128 v[170:173], v178 offset:1024
	ds_read_b128 v[174:177], v178 offset:2048
	ds_read_b128 v[178:181], v178 offset:3072
	s_add_u32 s26, s26, 0x40000
	s_addc_u32 s27, s27, 0
	s_mov_b32 m0, s33
	v_lshl_add_u64 v[224:225], s[26:27], 0, v[134:135]
	ds_read_b128 v[182:185], v153 offset:32768
	ds_read_b128 v[186:189], v153 offset:33792
	ds_read_b128 v[190:193], v153 offset:34816
	ds_read_b128 v[194:197], v153 offset:35840
	ds_read_b128 v[198:201], v153 offset:36864
	ds_read_b128 v[202:205], v153 offset:37888
	ds_read_b128 v[210:213], v153 offset:38912
	ds_read_b128 v[214:217], v153 offset:39936
	global_load_lds_dwordx4 v[224:225], off
	v_lshl_add_u64 v[224:225], s[26:27], 0, v[130:131]
	s_mov_b32 m0, s35
	s_nop 0
	global_load_lds_dwordx4 v[224:225], off
	s_waitcnt vmcnt(8) lgkmcnt(0)
	s_setprio 1
	s_barrier
	v_mfma_f32_16x16x32_bf16 v[124:127], v[144:147], v[182:185], v[124:127]
	v_mfma_f32_16x16x32_bf16 v[120:123], v[158:161], v[182:185], v[120:123]
	v_mfma_f32_16x16x32_bf16 v[116:119], v[144:147], v[190:193], v[116:119]
	v_mfma_f32_16x16x32_bf16 v[108:111], v[158:161], v[190:193], v[108:111]
	v_mfma_f32_16x16x32_bf16 v[100:103], v[144:147], v[198:201], v[100:103]
	v_mfma_f32_16x16x32_bf16 v[92:95], v[158:161], v[198:201], v[92:95]
	v_mfma_f32_16x16x32_bf16 v[84:87], v[144:147], v[210:213], v[84:87]
	v_mfma_f32_16x16x32_bf16 v[76:79], v[158:161], v[210:213], v[76:79]
	v_mfma_f32_16x16x32_bf16 v[124:127], v[154:157], v[186:189], v[124:127]
	v_mfma_f32_16x16x32_bf16 v[120:123], v[162:165], v[186:189], v[120:123]
	v_mfma_f32_16x16x32_bf16 v[116:119], v[154:157], v[194:197], v[116:119]
	v_mfma_f32_16x16x32_bf16 v[108:111], v[162:165], v[194:197], v[108:111]
	v_mfma_f32_16x16x32_bf16 v[100:103], v[154:157], v[202:205], v[100:103]
	v_mfma_f32_16x16x32_bf16 v[92:95], v[162:165], v[202:205], v[92:95]
	v_mfma_f32_16x16x32_bf16 v[84:87], v[154:157], v[214:217], v[84:87]
	v_mfma_f32_16x16x32_bf16 v[76:79], v[162:165], v[214:217], v[76:79]
	s_setprio 0
	s_setprio 1
	v_mfma_f32_16x16x32_bf16 v[112:115], v[166:169], v[182:185], v[112:115]
	v_mfma_f32_16x16x32_bf16 v[104:107], v[174:177], v[182:185], v[104:107]
	v_mfma_f32_16x16x32_bf16 v[96:99], v[166:169], v[190:193], v[96:99]
	v_mfma_f32_16x16x32_bf16 v[88:91], v[174:177], v[190:193], v[88:91]
	v_mfma_f32_16x16x32_bf16 v[80:83], v[166:169], v[198:201], v[80:83]
	v_mfma_f32_16x16x32_bf16 v[72:75], v[174:177], v[198:201], v[72:75]
	v_mfma_f32_16x16x32_bf16 v[68:71], v[166:169], v[210:213], v[68:71]
	v_mfma_f32_16x16x32_bf16 v[64:67], v[174:177], v[210:213], v[64:67]
	v_mfma_f32_16x16x32_bf16 v[112:115], v[170:173], v[186:189], v[112:115]
	v_mfma_f32_16x16x32_bf16 v[104:107], v[178:181], v[186:189], v[104:107]
	v_mfma_f32_16x16x32_bf16 v[96:99], v[170:173], v[194:197], v[96:99]
	v_mfma_f32_16x16x32_bf16 v[88:91], v[178:181], v[194:197], v[88:91]
	v_mfma_f32_16x16x32_bf16 v[80:83], v[170:173], v[202:205], v[80:83]
	v_mfma_f32_16x16x32_bf16 v[72:75], v[178:181], v[202:205], v[72:75]
	v_mfma_f32_16x16x32_bf16 v[68:71], v[170:173], v[214:217], v[68:71]
	v_mfma_f32_16x16x32_bf16 v[64:67], v[178:181], v[214:217], v[64:67]
	s_setprio 0
	s_barrier
; #define PG8_STAGE(bufoff, gbase, voff) do { _Pragma("unroll") for (int _i = 0; _i < 2; ++_i) \
;         __builtin_amdgcn_global_load_lds((const unsigned*)((const char*)(gbase) + (voff)[_i]), (LAS unsigned*)(lds + (bufoff) + ldsw + _i * 8192), 16, 0, 0); } while (0)
; #define PG8_LDA(dst, b, h) do { _Pragma("unroll") for (int m = 0; m < 4; ++m) _Pragma("unroll") for (int k = 0; k < 2; ++k) dst[m][k] = *(const LAS bf16x8*)(lds + PG8_SA(b, h) + aoff + m * 2048 + k * 1024); } while (0)
; #define PG8_MMA(ai, bj, At, Bt) do { __builtin_amdgcn_s_setprio(1); _Pragma("unroll") for (int m = 0; m < 4; ++m) _Pragma("unroll") for (int n = 0; n < 2; ++n) _Pragma("unroll") for (int k = 0; k < 2; ++k) \
;         acc[ai][bj][m][n] = __builtin_amdgcn_mfma_f32_16x16x32_bf16(Bt[n][k], At[m][k], acc[ai][bj][m][n], 0, 0, 0); __builtin_amdgcn_s_setprio(0); } while (0)
; #define PG8_WAIT_V(n) asm volatile("s_waitcnt vmcnt(" #n ")" ::: "memory")
; #define PG8_WAIT_L(n) asm volatile("s_waitcnt lgkmcnt(" #n ")" ::: "memory")
; #define PG8_BAR __builtin_amdgcn_s_barrier()
; #define PG8_SCHED __builtin_amdgcn_sched_barrier(0)
; template <class Epi, class Sched>
; __device__ __forceinline__ void gemm_phase(LAS unsigned char* lds, const Gemm g, const Sched& S, const Epi& E, const int wave_s) {
;     ...
;             PG8_LDA(At, 1, 1); PG8_STAGE(PG8_SB(1, 0), b3, voffB); PG8_STAGE(PG8_SB(1, 1), b3 + hstepB, voffB); PG8_STAGE(PG8_SA(1, 0), a3, voffA);
;             PG8_WAIT_V(8); PG8_WAIT_L(0); PG8_BAR; PG8_MMA(1, 0, At, B0); PG8_MMA(1, 1, At, B1); PG8_BAR; PG8_SCHED;
;         }
;         if (wr == 0) PG8_BAR;
	s_add_i32 s26, s55, s81
	v_lshl_add_u64 v[206:207], v[206:207], 0, s[12:13]
	s_mov_b32 m0, s26
	ds_read_b128 v[182:185], v153 offset:49152
	ds_read_b128 v[186:189], v153 offset:50176
	ds_read_b128 v[190:193], v153 offset:51200
	ds_read_b128 v[194:197], v153 offset:52224
	ds_read_b128 v[198:201], v153 offset:53248
	ds_read_b128 v[202:205], v153 offset:54272
	ds_read_b128 v[210:213], v153 offset:55296
	ds_read_b128 v[214:217], v153 offset:56320
	global_load_lds_dwordx4 v[206:207], off
	s_add_i32 m0, s26, 0x2000
	s_add_u32 s4, s4, 0x40080
	v_lshl_add_u64 v[206:207], v[218:219], 0, s[12:13]
	s_addc_u32 s5, s5, 0
	s_add_i32 s26, s57, s81
	global_load_lds_dwordx4 v[206:207], off
	v_lshl_add_u64 v[206:207], s[4:5], 0, v[132:133]
	s_mov_b32 m0, s26
	s_nop 0
	global_load_lds_dwordx4 v[206:207], off
	v_lshl_add_u64 v[206:207], s[4:5], 0, v[128:129]
	s_add_i32 m0, s26, 0x2000
	s_nop 0
	global_load_lds_dwordx4 v[206:207], off
	v_lshl_add_u64 v[206:207], v[220:221], 0, s[12:13]
	s_mov_b32 m0, s41
	s_nop 0
	global_load_lds_dwordx4 v[206:207], off
	v_lshl_add_u64 v[206:207], v[222:223], 0, s[12:13]
	s_mov_b32 m0, s42
	s_nop 0
	global_load_lds_dwordx4 v[206:207], off
	s_waitcnt vmcnt(8) lgkmcnt(0)
	s_setprio 1
	s_barrier
	v_mfma_f32_16x16x32_bf16 v[60:63], v[144:147], v[182:185], v[60:63]
	v_mfma_f32_16x16x32_bf16 v[56:59], v[158:161], v[182:185], v[56:59]
	v_mfma_f32_16x16x32_bf16 v[52:55], v[144:147], v[190:193], v[52:55]
	v_mfma_f32_16x16x32_bf16 v[44:47], v[158:161], v[190:193], v[44:47]
	v_mfma_f32_16x16x32_bf16 v[36:39], v[144:147], v[198:201], v[36:39]
	v_mfma_f32_16x16x32_bf16 v[28:31], v[158:161], v[198:201], v[28:31]
	v_mfma_f32_16x16x32_bf16 v[20:23], v[144:147], v[210:213], v[20:23]
	v_mfma_f32_16x16x32_bf16 v[12:15], v[158:161], v[210:213], v[12:15]
	v_mfma_f32_16x16x32_bf16 v[60:63], v[154:157], v[186:189], v[60:63]
	v_mfma_f32_16x16x32_bf16 v[56:59], v[162:165], v[186:189], v[56:59]
	v_mfma_f32_16x16x32_bf16 v[52:55], v[154:157], v[194:197], v[52:55]
	v_mfma_f32_16x16x32_bf16 v[44:47], v[162:165], v[194:197], v[44:47]
	v_mfma_f32_16x16x32_bf16 v[36:39], v[154:157], v[202:205], v[36:39]
	v_mfma_f32_16x16x32_bf16 v[28:31], v[162:165], v[202:205], v[28:31]
	v_mfma_f32_16x16x32_bf16 v[20:23], v[154:157], v[214:217], v[20:23]
	v_mfma_f32_16x16x32_bf16 v[12:15], v[162:165], v[214:217], v[12:15]
	s_setprio 0
	s_setprio 1
	v_mfma_f32_16x16x32_bf16 v[48:51], v[166:169], v[182:185], v[48:51]
	v_mfma_f32_16x16x32_bf16 v[40:43], v[174:177], v[182:185], v[40:43]
	v_mfma_f32_16x16x32_bf16 v[32:35], v[166:169], v[190:193], v[32:35]
	v_mfma_f32_16x16x32_bf16 v[24:27], v[174:177], v[190:193], v[24:27]
	v_mfma_f32_16x16x32_bf16 v[16:19], v[166:169], v[198:201], v[16:19]
	v_mfma_f32_16x16x32_bf16 v[8:11], v[174:177], v[198:201], v[8:11]
	v_mfma_f32_16x16x32_bf16 v[4:7], v[166:169], v[210:213], v[4:7]
	v_mfma_f32_16x16x32_bf16 v[0:3], v[174:177], v[210:213], v[0:3]
	v_mfma_f32_16x16x32_bf16 v[48:51], v[170:173], v[186:189], v[48:51]
	v_mfma_f32_16x16x32_bf16 v[40:43], v[178:181], v[186:189], v[40:43]
	v_mfma_f32_16x16x32_bf16 v[32:35], v[170:173], v[194:197], v[32:35]
	v_mfma_f32_16x16x32_bf16 v[24:27], v[178:181], v[194:197], v[24:27]
	v_mfma_f32_16x16x32_bf16 v[16:19], v[170:173], v[202:205], v[16:19]
	v_mfma_f32_16x16x32_bf16 v[8:11], v[178:181], v[202:205], v[8:11]
	v_mfma_f32_16x16x32_bf16 v[4:7], v[170:173], v[214:217], v[4:7]
	v_mfma_f32_16x16x32_bf16 v[0:3], v[178:181], v[214:217], v[0:3]
	s_setprio 0
	s_barrier
	s_add_i32 s54, s54, 2
	s_add_u32 s24, s24, 0x100
	s_addc_u32 s25, s25, 0
	s_add_u32 s52, s52, 0x100
	s_addc_u32 s53, s53, 0
	s_cmp_gt_u32 s54, 13
	s_cbranch_scc0 .LBB0_194
	s_and_b64 vcc, exec, s[14:15]
	s_cbranch_vccz .LBB0_197
	s_barrier

; #define PG8_STAGE(bufoff, gbase, voff) do { _Pragma("unroll") for (int _i = 0; _i < 2; ++_i) \
;         __builtin_amdgcn_global_load_lds((const unsigned*)((const char*)(gbase) + (voff)[_i]), (LAS unsigned*)(lds + (bufoff) + ldsw + _i * 8192), 16, 0, 0); } while (0)
; #define PG8_LDA(dst, b, h) do { _Pragma("unroll") for (int m = 0; m < 4; ++m) _Pragma("unroll") for (int k = 0; k < 2; ++k) dst[m][k] = *(const LAS bf16x8*)(lds + PG8_SA(b, h) + aoff + m * 2048 + k * 1024); } while (0)
; #define PG8_LDB(dst, b, h) do { _Pragma("unroll") for (int n = 0; n < 2; ++n) _Pragma("unroll") for (int k = 0; k < 2; ++k) dst[n][k] = *(const LAS bf16x8*)(lds + PG8_SB(b, h) + boff + n * 2048 + k * 1024); } while (0)
; #define PG8_MMA(ai, bj, At, Bt) do { __builtin_amdgcn_s_setprio(1); _Pragma("unroll") for (int m = 0; m < 4; ++m) _Pragma("unroll") for (int n = 0; n < 2; ++n) _Pragma("unroll") for (int k = 0; k < 2; ++k) \
;         acc[ai][bj][m][n] = __builtin_amdgcn_mfma_f32_16x16x32_bf16(Bt[n][k], At[m][k], acc[ai][bj][m][n], 0, 0, 0); __builtin_amdgcn_s_setprio(0); } while (0)
; #define PG8_WAIT_V(n) asm volatile("s_waitcnt vmcnt(" #n ")" ::: "memory")
; #define PG8_WAIT_L(n) asm volatile("s_waitcnt lgkmcnt(" #n ")" ::: "memory")
; #define PG8_BAR __builtin_amdgcn_s_barrier()
; #define PG8_SCHED __builtin_amdgcn_sched_barrier(0)
; template <class Epi, class Sched>
; __device__ __forceinline__ void gemm_phase(LAS unsigned char* lds, const Gemm g, const Sched& S, const Epi& E, const int wave_s) {
;     ...
;             const bool last = (t == nt - 2);
;             const char* a1 = cA + (size_t)(t + 1) * kstep;
;             const char* a2 = last ? nA : cA + (size_t)(t + 2) * kstep; const char* b2 = last ? nB : cB + (size_t)(t + 2) * kstep;
;             const char* a3 = a2 + kstep; const char* b3 = b2 + kstep;
;             PG8_LDB(B0, 0, 0); PG8_LDB(B1, 0, 1); PG8_SCHED; PG8_LDA(At, 0, 0); PG8_STAGE(PG8_SA(1, 1), a1 + hstepA, voffA);
;             PG8_WAIT_V(8); PG8_WAIT_L(0); PG8_BAR; PG8_MMA(0, 0, At, B0); PG8_MMA(0, 1, At, B1); PG8_BAR; PG8_SCHED;
;             PG8_LDA(At, 0, 1); PG8_STAGE(PG8_SB(0, 0), b2, voffB); PG8_STAGE(PG8_SB(0, 1), b2 + hstepB, voffB); PG8_STAGE(PG8_SA(0, 0), a2, voffA);
.LBB0_375:
	ds_read_b128 v[158:161], v155
	ds_read_b128 v[162:165], v155 offset:1024
	ds_read_b128 v[166:169], v155 offset:2048
	ds_read_b128 v[170:173], v155 offset:3072
	ds_read_b128 v[174:177], v156
	ds_read_b128 v[178:181], v156 offset:1024
	ds_read_b128 v[182:185], v156 offset:2048
	ds_read_b128 v[186:189], v156 offset:3072
	s_add_u32 s4, s22, 0x100
	s_addc_u32 s5, s23, 0
	s_cmp_eq_u32 s48, 2
	s_cselect_b32 s25, s19, s5
	s_cselect_b32 s24, s18, s4
	s_cselect_b32 s9, s21, s47
	s_cselect_b32 s8, s20, s46
	v_lshl_add_u64 v[150:151], s[22:23], 0, v[142:143]
	s_add_i32 m0, s27, 0xc000
	ds_read_b128 v[190:193], v157
	ds_read_b128 v[194:197], v157 offset:1024
	ds_read_b128 v[198:201], v157 offset:2048
	ds_read_b128 v[202:205], v157 offset:3072
	ds_read_b128 v[210:213], v157 offset:4096
	ds_read_b128 v[214:217], v157 offset:5120
	ds_read_b128 v[218:221], v157 offset:6144
	ds_read_b128 v[222:225], v157 offset:7168
	global_load_lds_dwordx4 v[150:151], off
	v_lshl_add_u64 v[150:151], s[22:23], 0, v[144:145]
	s_add_i32 m0, s27, 0xe000
	s_nop 0
	global_load_lds_dwordx4 v[150:151], off
	s_waitcnt vmcnt(8) lgkmcnt(0)
	s_setprio 1
	s_barrier
	v_mfma_f32_16x16x32_bf16 v[124:127], v[158:161], v[190:193], v[124:127]
	v_mfma_f32_16x16x32_bf16 v[120:123], v[166:169], v[190:193], v[120:123]
	v_mfma_f32_16x16x32_bf16 v[108:111], v[158:161], v[198:201], v[108:111]
	v_mfma_f32_16x16x32_bf16 v[104:107], v[166:169], v[198:201], v[104:107]
	v_mfma_f32_16x16x32_bf16 v[92:95], v[158:161], v[210:213], v[92:95]
	v_mfma_f32_16x16x32_bf16 v[88:91], v[166:169], v[210:213], v[88:91]
	v_mfma_f32_16x16x32_bf16 v[76:79], v[158:161], v[218:221], v[76:79]
	v_mfma_f32_16x16x32_bf16 v[72:75], v[166:169], v[218:221], v[72:75]
	v_mfma_f32_16x16x32_bf16 v[124:127], v[162:165], v[194:197], v[124:127]
	v_mfma_f32_16x16x32_bf16 v[120:123], v[170:173], v[194:197], v[120:123]
	v_mfma_f32_16x16x32_bf16 v[108:111], v[162:165], v[202:205], v[108:111]
	v_mfma_f32_16x16x32_bf16 v[104:107], v[170:173], v[202:205], v[104:107]
	v_mfma_f32_16x16x32_bf16 v[92:95], v[162:165], v[214:217], v[92:95]
	v_mfma_f32_16x16x32_bf16 v[88:91], v[170:173], v[214:217], v[88:91]
	v_mfma_f32_16x16x32_bf16 v[76:79], v[162:165], v[222:225], v[76:79]
	v_mfma_f32_16x16x32_bf16 v[72:75], v[170:173], v[222:225], v[72:75]
	s_setprio 0
	s_setprio 1
	v_mfma_f32_16x16x32_bf16 v[116:119], v[174:177], v[190:193], v[116:119]
	v_mfma_f32_16x16x32_bf16 v[112:115], v[182:185], v[190:193], v[112:115]
	v_mfma_f32_16x16x32_bf16 v[100:103], v[174:177], v[198:201], v[100:103]
	v_mfma_f32_16x16x32_bf16 v[96:99], v[182:185], v[198:201], v[96:99]
	v_mfma_f32_16x16x32_bf16 v[84:87], v[174:177], v[210:213], v[84:87]
	v_mfma_f32_16x16x32_bf16 v[80:83], v[182:185], v[210:213], v[80:83]
	v_mfma_f32_16x16x32_bf16 v[68:71], v[174:177], v[218:221], v[68:71]
	v_mfma_f32_16x16x32_bf16 v[64:67], v[182:185], v[218:221], v[64:67]
	v_mfma_f32_16x16x32_bf16 v[116:119], v[178:181], v[194:197], v[116:119]
	v_mfma_f32_16x16x32_bf16 v[112:115], v[186:189], v[194:197], v[112:115]
	v_mfma_f32_16x16x32_bf16 v[100:103], v[178:181], v[202:205], v[100:103]
	v_mfma_f32_16x16x32_bf16 v[96:99], v[186:189], v[202:205], v[96:99]
	v_mfma_f32_16x16x32_bf16 v[84:87], v[178:181], v[214:217], v[84:87]
	v_mfma_f32_16x16x32_bf16 v[80:83], v[186:189], v[214:217], v[80:83]
	v_mfma_f32_16x16x32_bf16 v[68:71], v[178:181], v[222:225], v[68:71]
	v_mfma_f32_16x16x32_bf16 v[64:67], v[186:189], v[222:225], v[64:67]
	s_setprio 0
	s_barrier
	s_add_i32 s22, s39, s81
	v_lshl_add_u64 v[150:151], s[8:9], 0, v[130:131]
	s_mov_b32 m0, s22
	ds_read_b128 v[190:193], v157 offset:16384
	ds_read_b128 v[194:197], v157 offset:17408
	ds_read_b128 v[198:201], v157 offset:18432
	ds_read_b128 v[202:205], v157 offset:19456
	ds_read_b128 v[210:213], v157 offset:20480
	ds_read_b128 v[214:217], v157 offset:21504
	ds_read_b128 v[218:221], v157 offset:22528
	ds_read_b128 v[222:225], v157 offset:23552
	global_load_lds_dwordx4 v[150:151], off
	s_add_i32 m0, s22, 0x2000
	s_add_u32 s22, s8, 0x18000
	v_lshl_add_u64 v[206:207], s[8:9], 0, v[134:135]
	s_addc_u32 s23, s9, 0
	s_add_i32 s49, s40, s81
	global_load_lds_dwordx4 v[206:207], off
	v_lshl_add_u64 v[226:227], s[22:23], 0, v[130:131]
	s_mov_b32 m0, s49
	v_lshl_add_u64 v[228:229], s[24:25], 0, v[132:133]
	global_load_lds_dwordx4 v[226:227], off
	v_lshl_add_u64 v[226:227], s[22:23], 0, v[134:135]
	s_add_i32 m0, s49, 0x2000
	s_nop 0
	global_load_lds_dwordx4 v[226:227], off
	v_lshl_add_u64 v[226:227], s[24:25], 0, v[128:129]
	s_mov_b32 m0, s27
	s_nop 0
	global_load_lds_dwordx4 v[226:227], off
	s_mov_b32 m0, s28
	s_nop 0
	global_load_lds_dwordx4 v[228:229], off
	s_waitcnt vmcnt(8) lgkmcnt(0)
	s_setprio 1
	s_barrier
; #define PG8_STAGE(bufoff, gbase, voff) do { _Pragma("unroll") for (int _i = 0; _i < 2; ++_i) \
;         __builtin_amdgcn_global_load_lds((const unsigned*)((const char*)(gbase) + (voff)[_i]), (LAS unsigned*)(lds + (bufoff) + ldsw + _i * 8192), 16, 0, 0); } while (0)
; #define PG8_LDA(dst, b, h) do { _Pragma("unroll") for (int m = 0; m < 4; ++m) _Pragma("unroll") for (int k = 0; k < 2; ++k) dst[m][k] = *(const LAS bf16x8*)(lds + PG8_SA(b, h) + aoff + m * 2048 + k * 1024); } while (0)
; #define PG8_LDB(dst, b, h) do { _Pragma("unroll") for (int n = 0; n < 2; ++n) _Pragma("unroll") for (int k = 0; k < 2; ++k) dst[n][k] = *(const LAS bf16x8*)(lds + PG8_SB(b, h) + boff + n * 2048 + k * 1024); } while (0)
; #define PG8_MMA(ai, bj, At, Bt) do { __builtin_amdgcn_s_setprio(1); _Pragma("unroll") for (int m = 0; m < 4; ++m) _Pragma("unroll") for (int n = 0; n < 2; ++n) _Pragma("unroll") for (int k = 0; k < 2; ++k) \
;         acc[ai][bj][m][n] = __builtin_amdgcn_mfma_f32_16x16x32_bf16(Bt[n][k], At[m][k], acc[ai][bj][m][n], 0, 0, 0); __builtin_amdgcn_s_setprio(0); } while (0)
; #define PG8_WAIT_V(n) asm volatile("s_waitcnt vmcnt(" #n ")" ::: "memory")
; #define PG8_WAIT_L(n) asm volatile("s_waitcnt lgkmcnt(" #n ")" ::: "memory")
; #define PG8_BAR __builtin_amdgcn_s_barrier()
; #define PG8_SCHED __builtin_amdgcn_sched_barrier(0)
; template <class Epi, class Sched>
; __device__ __forceinline__ void gemm_phase(LAS unsigned char* lds, const Gemm g, const Sched& S, const Epi& E, const int wave_s) {
;     ...
;             PG8_WAIT_V(8); PG8_WAIT_L(0); PG8_BAR; PG8_MMA(1, 0, At, B0); PG8_MMA(1, 1, At, B1); PG8_BAR; PG8_SCHED;
;             PG8_LDB(B0, 1, 0); PG8_LDB(B1, 1, 1); PG8_SCHED; PG8_LDA(At, 1, 0); PG8_STAGE(PG8_SA(0, 1), a2 + hstepA, voffA);
;             PG8_WAIT_V(8); PG8_WAIT_L(0); PG8_BAR; PG8_MMA(0, 0, At, B0); PG8_MMA(0, 1, At, B1); PG8_BAR; PG8_SCHED;
	v_mfma_f32_16x16x32_bf16 v[60:63], v[158:161], v[190:193], v[60:63]
	v_mfma_f32_16x16x32_bf16 v[56:59], v[166:169], v[190:193], v[56:59]
	v_mfma_f32_16x16x32_bf16 v[44:47], v[158:161], v[198:201], v[44:47]
	v_mfma_f32_16x16x32_bf16 v[40:43], v[166:169], v[198:201], v[40:43]
	v_mfma_f32_16x16x32_bf16 v[28:31], v[158:161], v[210:213], v[28:31]
	v_mfma_f32_16x16x32_bf16 v[24:27], v[166:169], v[210:213], v[24:27]
	v_mfma_f32_16x16x32_bf16 v[12:15], v[158:161], v[218:221], v[12:15]
	v_mfma_f32_16x16x32_bf16 v[8:11], v[166:169], v[218:221], v[8:11]
	v_mfma_f32_16x16x32_bf16 v[60:63], v[162:165], v[194:197], v[60:63]
	v_mfma_f32_16x16x32_bf16 v[56:59], v[170:173], v[194:197], v[56:59]
	v_mfma_f32_16x16x32_bf16 v[44:47], v[162:165], v[202:205], v[44:47]
	v_mfma_f32_16x16x32_bf16 v[40:43], v[170:173], v[202:205], v[40:43]
	v_mfma_f32_16x16x32_bf16 v[28:31], v[162:165], v[214:217], v[28:31]
	v_mfma_f32_16x16x32_bf16 v[24:27], v[170:173], v[214:217], v[24:27]
	v_mfma_f32_16x16x32_bf16 v[12:15], v[162:165], v[222:225], v[12:15]
	v_mfma_f32_16x16x32_bf16 v[8:11], v[170:173], v[222:225], v[8:11]
	s_setprio 0
	s_setprio 1
	v_mfma_f32_16x16x32_bf16 v[52:55], v[174:177], v[190:193], v[52:55]
	v_mfma_f32_16x16x32_bf16 v[48:51], v[182:185], v[190:193], v[48:51]
	v_mfma_f32_16x16x32_bf16 v[36:39], v[174:177], v[198:201], v[36:39]
	v_mfma_f32_16x16x32_bf16 v[32:35], v[182:185], v[198:201], v[32:35]
	v_mfma_f32_16x16x32_bf16 v[20:23], v[174:177], v[210:213], v[20:23]
	v_mfma_f32_16x16x32_bf16 v[16:19], v[182:185], v[210:213], v[16:19]
	v_mfma_f32_16x16x32_bf16 v[4:7], v[174:177], v[218:221], v[4:7]
	v_mfma_f32_16x16x32_bf16 v[0:3], v[182:185], v[218:221], v[0:3]
	v_mfma_f32_16x16x32_bf16 v[52:55], v[178:181], v[194:197], v[52:55]
	v_mfma_f32_16x16x32_bf16 v[48:51], v[186:189], v[194:197], v[48:51]
	v_mfma_f32_16x16x32_bf16 v[36:39], v[178:181], v[202:205], v[36:39]
	v_mfma_f32_16x16x32_bf16 v[32:35], v[186:189], v[202:205], v[32:35]
	v_mfma_f32_16x16x32_bf16 v[20:23], v[178:181], v[214:217], v[20:23]
	v_mfma_f32_16x16x32_bf16 v[16:19], v[186:189], v[214:217], v[16:19]
	v_mfma_f32_16x16x32_bf16 v[4:7], v[178:181], v[222:225], v[4:7]
	v_mfma_f32_16x16x32_bf16 v[0:3], v[186:189], v[222:225], v[0:3]
	s_setprio 0
	s_barrier
	s_add_i32 s49, 0, 0x18000
	v_add_u32_e32 v136, s49, v153
	s_add_i32 s50, 0, 0x1c000
	ds_read_b128 v[158:161], v136
	ds_read_b128 v[162:165], v136 offset:1024
	ds_read_b128 v[166:169], v136 offset:2048
	ds_read_b128 v[170:173], v136 offset:3072
	v_add_u32_e32 v136, s50, v153
	ds_read_b128 v[174:177], v136
	ds_read_b128 v[178:181], v136 offset:1024
	ds_read_b128 v[182:185], v136 offset:2048
	ds_read_b128 v[186:189], v136 offset:3072
	s_add_u32 s22, s24, 0xf0000
	s_addc_u32 s23, s25, 0
	s_mov_b32 m0, s29
	v_lshl_add_u64 v[230:231], s[22:23], 0, v[128:129]
	ds_read_b128 v[190:193], v157 offset:32768
	ds_read_b128 v[194:197], v157 offset:33792
	ds_read_b128 v[198:201], v157 offset:34816
	ds_read_b128 v[202:205], v157 offset:35840
	ds_read_b128 v[210:213], v157 offset:36864
	ds_read_b128 v[214:217], v157 offset:37888
	ds_read_b128 v[218:221], v157 offset:38912
	ds_read_b128 v[222:225], v157 offset:39936
	global_load_lds_dwordx4 v[230:231], off
	v_lshl_add_u64 v[230:231], s[22:23], 0, v[132:133]
	s_mov_b32 m0, s30
	s_nop 0
	global_load_lds_dwordx4 v[230:231], off
	s_waitcnt vmcnt(8) lgkmcnt(0)
	s_setprio 1
	s_barrier
	v_mfma_f32_16x16x32_bf16 v[124:127], v[158:161], v[190:193], v[124:127]
	v_mfma_f32_16x16x32_bf16 v[120:123], v[166:169], v[190:193], v[120:123]
	v_mfma_f32_16x16x32_bf16 v[108:111], v[158:161], v[198:201], v[108:111]
	v_mfma_f32_16x16x32_bf16 v[104:107], v[166:169], v[198:201], v[104:107]
	v_mfma_f32_16x16x32_bf16 v[92:95], v[158:161], v[210:213], v[92:95]
	v_mfma_f32_16x16x32_bf16 v[88:91], v[166:169], v[210:213], v[88:91]
	v_mfma_f32_16x16x32_bf16 v[76:79], v[158:161], v[218:221], v[76:79]
	v_mfma_f32_16x16x32_bf16 v[72:75], v[166:169], v[218:221], v[72:75]
	v_mfma_f32_16x16x32_bf16 v[124:127], v[162:165], v[194:197], v[124:127]
	v_mfma_f32_16x16x32_bf16 v[120:123], v[170:173], v[194:197], v[120:123]
	v_mfma_f32_16x16x32_bf16 v[108:111], v[162:165], v[202:205], v[108:111]
	v_mfma_f32_16x16x32_bf16 v[104:107], v[170:173], v[202:205], v[104:107]
	v_mfma_f32_16x16x32_bf16 v[92:95], v[162:165], v[214:217], v[92:95]
	v_mfma_f32_16x16x32_bf16 v[88:91], v[170:173], v[214:217], v[88:91]
	v_mfma_f32_16x16x32_bf16 v[76:79], v[162:165], v[222:225], v[76:79]
	v_mfma_f32_16x16x32_bf16 v[72:75], v[170:173], v[222:225], v[72:75]
	s_setprio 0
	s_setprio 1
	v_mfma_f32_16x16x32_bf16 v[116:119], v[174:177], v[190:193], v[116:119]
	v_mfma_f32_16x16x32_bf16 v[112:115], v[182:185], v[190:193], v[112:115]
	v_mfma_f32_16x16x32_bf16 v[100:103], v[174:177], v[198:201], v[100:103]
	v_mfma_f32_16x16x32_bf16 v[96:99], v[182:185], v[198:201], v[96:99]
	v_mfma_f32_16x16x32_bf16 v[84:87], v[174:177], v[210:213], v[84:87]
	v_mfma_f32_16x16x32_bf16 v[80:83], v[182:185], v[210:213], v[80:83]
	v_mfma_f32_16x16x32_bf16 v[68:71], v[174:177], v[218:221], v[68:71]
	v_mfma_f32_16x16x32_bf16 v[64:67], v[182:185], v[218:221], v[64:67]
	v_mfma_f32_16x16x32_bf16 v[116:119], v[178:181], v[194:197], v[116:119]
	v_mfma_f32_16x16x32_bf16 v[112:115], v[186:189], v[194:197], v[112:115]
	v_mfma_f32_16x16x32_bf16 v[100:103], v[178:181], v[202:205], v[100:103]
	v_mfma_f32_16x16x32_bf16 v[96:99], v[186:189], v[202:205], v[96:99]
	v_mfma_f32_16x16x32_bf16 v[84:87], v[178:181], v[214:217], v[84:87]
	v_mfma_f32_16x16x32_bf16 v[80:83], v[186:189], v[214:217], v[80:83]
	v_mfma_f32_16x16x32_bf16 v[68:71], v[178:181], v[222:225], v[68:71]
	v_mfma_f32_16x16x32_bf16 v[64:67], v[186:189], v[222:225], v[64:67]
	s_setprio 0
	s_barrier
; #define PG8_STAGE(bufoff, gbase, voff) do { _Pragma("unroll") for (int _i = 0; _i < 2; ++_i) \
;         __builtin_amdgcn_global_load_lds((const unsigned*)((const char*)(gbase) + (voff)[_i]), (LAS unsigned*)(lds + (bufoff) + ldsw + _i * 8192), 16, 0, 0); } while (0)
; #define PG8_LDA(dst, b, h) do { _Pragma("unroll") for (int m = 0; m < 4; ++m) _Pragma("unroll") for (int k = 0; k < 2; ++k) dst[m][k] = *(const LAS bf16x8*)(lds + PG8_SA(b, h) + aoff + m * 2048 + k * 1024); } while (0)
; #define PG8_MMA(ai, bj, At, Bt) do { __builtin_amdgcn_s_setprio(1); _Pragma("unroll") for (int m = 0; m < 4; ++m) _Pragma("unroll") for (int n = 0; n < 2; ++n) _Pragma("unroll") for (int k = 0; k < 2; ++k) \
;         acc[ai][bj][m][n] = __builtin_amdgcn_mfma_f32_16x16x32_bf16(Bt[n][k], At[m][k], acc[ai][bj][m][n], 0, 0, 0); __builtin_amdgcn_s_setprio(0); } while (0)
; #define PG8_WAIT_V(n) asm volatile("s_waitcnt vmcnt(" #n ")" ::: "memory")
; #define PG8_WAIT_L(n) asm volatile("s_waitcnt lgkmcnt(" #n ")" ::: "memory")
; #define PG8_BAR __builtin_amdgcn_s_barrier()
; #define PG8_SCHED __builtin_amdgcn_sched_barrier(0)
; template <class Epi, class Sched>
; __device__ __forceinline__ void gemm_phase(LAS unsigned char* lds, const Gemm g, const Sched& S, const Epi& E, const int wave_s) {
;     ...
;             PG8_LDA(At, 1, 1); PG8_STAGE(PG8_SB(1, 0), b3, voffB); PG8_STAGE(PG8_SB(1, 1), b3 + hstepB, voffB); PG8_STAGE(PG8_SA(1, 0), a3, voffA);
;             PG8_WAIT_V(8); PG8_WAIT_L(0); PG8_BAR; PG8_MMA(1, 0, At, B0); PG8_MMA(1, 1, At, B1); PG8_BAR; PG8_SCHED;
;         }
;         if (wr == 0) PG8_BAR;
	s_add_i32 s22, s49, s81
	v_lshl_add_u64 v[150:151], v[150:151], 0, s[14:15]
	s_mov_b32 m0, s22
	ds_read_b128 v[190:193], v157 offset:49152
	ds_read_b128 v[194:197], v157 offset:50176
	ds_read_b128 v[198:201], v157 offset:51200
	ds_read_b128 v[202:205], v157 offset:52224
	ds_read_b128 v[210:213], v157 offset:53248
	ds_read_b128 v[214:217], v157 offset:54272
	ds_read_b128 v[218:221], v157 offset:55296
	ds_read_b128 v[222:225], v157 offset:56320
	global_load_lds_dwordx4 v[150:151], off
	s_add_i32 m0, s22, 0x2000
	s_add_u32 s8, s8, 0x18080
	v_lshl_add_u64 v[150:151], v[206:207], 0, s[14:15]
	s_addc_u32 s9, s9, 0
	s_add_i32 s22, s50, s81
	global_load_lds_dwordx4 v[150:151], off
	v_lshl_add_u64 v[150:151], s[8:9], 0, v[130:131]
	s_mov_b32 m0, s22
	s_nop 0
	global_load_lds_dwordx4 v[150:151], off
	v_lshl_add_u64 v[150:151], s[8:9], 0, v[134:135]
	s_add_i32 m0, s22, 0x2000
	s_nop 0
	global_load_lds_dwordx4 v[150:151], off
	v_lshl_add_u64 v[150:151], v[226:227], 0, s[14:15]
	s_mov_b32 m0, s33
	s_nop 0
	global_load_lds_dwordx4 v[150:151], off
	v_lshl_add_u64 v[150:151], v[228:229], 0, s[14:15]
	s_mov_b32 m0, s34
	s_nop 0
	global_load_lds_dwordx4 v[150:151], off
	s_waitcnt vmcnt(8) lgkmcnt(0)
	s_setprio 1
	s_barrier
	v_mfma_f32_16x16x32_bf16 v[60:63], v[158:161], v[190:193], v[60:63]
	v_mfma_f32_16x16x32_bf16 v[56:59], v[166:169], v[190:193], v[56:59]
	v_mfma_f32_16x16x32_bf16 v[44:47], v[158:161], v[198:201], v[44:47]
	v_mfma_f32_16x16x32_bf16 v[40:43], v[166:169], v[198:201], v[40:43]
	v_mfma_f32_16x16x32_bf16 v[28:31], v[158:161], v[210:213], v[28:31]
	v_mfma_f32_16x16x32_bf16 v[24:27], v[166:169], v[210:213], v[24:27]
	v_mfma_f32_16x16x32_bf16 v[12:15], v[158:161], v[218:221], v[12:15]
	v_mfma_f32_16x16x32_bf16 v[8:11], v[166:169], v[218:221], v[8:11]
	v_mfma_f32_16x16x32_bf16 v[60:63], v[162:165], v[194:197], v[60:63]
	v_mfma_f32_16x16x32_bf16 v[56:59], v[170:173], v[194:197], v[56:59]
	v_mfma_f32_16x16x32_bf16 v[44:47], v[162:165], v[202:205], v[44:47]
	v_mfma_f32_16x16x32_bf16 v[40:43], v[170:173], v[202:205], v[40:43]
	v_mfma_f32_16x16x32_bf16 v[28:31], v[162:165], v[214:217], v[28:31]
	v_mfma_f32_16x16x32_bf16 v[24:27], v[170:173], v[214:217], v[24:27]
	v_mfma_f32_16x16x32_bf16 v[12:15], v[162:165], v[222:225], v[12:15]
	v_mfma_f32_16x16x32_bf16 v[8:11], v[170:173], v[222:225], v[8:11]
	s_setprio 0
	s_setprio 1
	v_mfma_f32_16x16x32_bf16 v[52:55], v[174:177], v[190:193], v[52:55]
	v_mfma_f32_16x16x32_bf16 v[48:51], v[182:185], v[190:193], v[48:51]
	v_mfma_f32_16x16x32_bf16 v[36:39], v[174:177], v[198:201], v[36:39]
	v_mfma_f32_16x16x32_bf16 v[32:35], v[182:185], v[198:201], v[32:35]
	v_mfma_f32_16x16x32_bf16 v[20:23], v[174:177], v[210:213], v[20:23]
	v_mfma_f32_16x16x32_bf16 v[16:19], v[182:185], v[210:213], v[16:19]
	v_mfma_f32_16x16x32_bf16 v[4:7], v[174:177], v[218:221], v[4:7]
	v_mfma_f32_16x16x32_bf16 v[0:3], v[182:185], v[218:221], v[0:3]
	v_mfma_f32_16x16x32_bf16 v[52:55], v[178:181], v[194:197], v[52:55]
	v_mfma_f32_16x16x32_bf16 v[48:51], v[186:189], v[194:197], v[48:51]
	v_mfma_f32_16x16x32_bf16 v[36:39], v[178:181], v[202:205], v[36:39]
	v_mfma_f32_16x16x32_bf16 v[32:35], v[186:189], v[202:205], v[32:35]
	v_mfma_f32_16x16x32_bf16 v[20:23], v[178:181], v[214:217], v[20:23]
	v_mfma_f32_16x16x32_bf16 v[16:19], v[186:189], v[214:217], v[16:19]
	v_mfma_f32_16x16x32_bf16 v[4:7], v[178:181], v[222:225], v[4:7]
	v_mfma_f32_16x16x32_bf16 v[0:3], v[186:189], v[222:225], v[0:3]
	s_setprio 0
	s_barrier
	s_add_i32 s48, s48, 2
	s_add_u32 s46, s46, 0x100
	s_addc_u32 s47, s47, 0
	s_cmp_gt_u32 s48, 3
	s_mov_b64 s[22:23], s[4:5]
	s_cbranch_scc0 .LBB0_375
	s_and_b64 vcc, exec, s[16:17]
	s_cbranch_vccz .LBB0_378
	s_barrier

; #define PG8_STAGE(bufoff, gbase, voff) do { _Pragma("unroll") for (int _i = 0; _i < 2; ++_i) \
;         __builtin_amdgcn_global_load_lds((const unsigned*)((const char*)(gbase) + (voff)[_i]), (LAS unsigned*)(lds + (bufoff) + ldsw + _i * 8192), 16, 0, 0); } while (0)
; #define PG8_LDA(dst, b, h) do { _Pragma("unroll") for (int m = 0; m < 4; ++m) _Pragma("unroll") for (int k = 0; k < 2; ++k) dst[m][k] = *(const LAS bf16x8*)(lds + PG8_SA(b, h) + aoff + m * 2048 + k * 1024); } while (0)
; #define PG8_LDB(dst, b, h) do { _Pragma("unroll") for (int n = 0; n < 2; ++n) _Pragma("unroll") for (int k = 0; k < 2; ++k) dst[n][k] = *(const LAS bf16x8*)(lds + PG8_SB(b, h) + boff + n * 2048 + k * 1024); } while (0)
; #define PG8_MMA(ai, bj, At, Bt) do { __builtin_amdgcn_s_setprio(1); _Pragma("unroll") for (int m = 0; m < 4; ++m) _Pragma("unroll") for (int n = 0; n < 2; ++n) _Pragma("unroll") for (int k = 0; k < 2; ++k) \
;         acc[ai][bj][m][n] = __builtin_amdgcn_mfma_f32_16x16x32_bf16(Bt[n][k], At[m][k], acc[ai][bj][m][n], 0, 0, 0); __builtin_amdgcn_s_setprio(0); } while (0)
; #define PG8_WAIT_V(n) asm volatile("s_waitcnt vmcnt(" #n ")" ::: "memory")
; #define PG8_BAR __builtin_amdgcn_s_barrier()
; template <class Epi, class Sched>
; __device__ __forceinline__ void gemm_phase(LAS unsigned char* lds, const Gemm g, const Sched& S, const Epi& E, const int wave_s) {
;     ...
;         const bool has_next = S.next(ui + 1, nxt);
;         const char* nA = has_next ? (const char*)g.A + (size_t)nxt.pm * tstepA + (size_t)nxt.acol * 2 : cA; const char* nB = has_next ? (const char*)g.Bt + (size_t)nxt.pn * tstepB : cB;
; #pragma unroll 1
;         for (int t = 0; t < nt; t += 2) {
;             const bool last = (t == nt - 2);
;             const char* a1 = cA + (size_t)(t + 1) * kstep;
;             const char* a2 = last ? nA : cA + (size_t)(t + 2) * kstep; const char* b2 = last ? nB : cB + (size_t)(t + 2) * kstep;
;             const char* a3 = a2 + kstep; const char* b3 = b2 + kstep;
;             PG8_LDB(B0, 0, 0); PG8_LDB(B1, 0, 1); PG8_SCHED; PG8_LDA(At, 0, 0); PG8_STAGE(PG8_SA(1, 1), a1 + hstepA, voffA);
;             PG8_WAIT_V(8); PG8_WAIT_L(0); PG8_BAR; PG8_MMA(0, 0, At, B0); PG8_MMA(0, 1, At, B1); PG8_BAR; PG8_SCHED;
;             PG8_LDA(At, 0, 1); PG8_STAGE(PG8_SB(0, 0), b2, voffB); PG8_STAGE(PG8_SB(0, 1), b2 + hstepB, voffB); PG8_STAGE(PG8_SA(0, 0), a2, voffA);
.LBB0_417:
	s_add_u32 s39, s36, s38
	s_addc_u32 s44, s37, 0
	s_add_u32 s42, s39, 0x100
	s_addc_u32 s43, s44, 0
	s_and_b64 s[40:41], s[4:5], exec
	s_cselect_b32 s41, s29, s43
	s_cselect_b32 s40, s28, s42
	s_add_u32 s38, s34, s38
	s_addc_u32 s42, s35, 0
	s_add_u32 s38, s38, 0x100
	s_addc_u32 s42, s42, 0
	s_and_b64 s[4:5], s[4:5], exec
	s_cselect_b32 s43, s27, s42
	s_cselect_b32 s42, s68, s38
	s_add_u32 s46, s39, 0xf0080
	ds_read_b128 v[148:151], v145
	ds_read_b128 v[152:155], v145 offset:1024
	ds_read_b128 v[156:159], v145 offset:2048
	ds_read_b128 v[160:163], v145 offset:3072
	ds_read_b128 v[164:167], v146
	ds_read_b128 v[168:171], v146 offset:1024
	ds_read_b128 v[172:175], v146 offset:2048
	ds_read_b128 v[176:179], v146 offset:3072
	s_addc_u32 s47, s44, 0
	s_add_i32 s76, s59, s81
	s_add_i32 m0, s49, 0xc000
	s_add_i32 s79, s49, 0xe000
	s_add_i32 s73, s76, 0x2000
	s_add_u32 s44, s42, 0x10000
	s_addc_u32 s45, s43, 0
	s_add_i32 s75, s60, s81
	s_add_i32 s74, s75, 0x2000
	s_add_i32 s72, 0, 0x18000
	s_add_i32 s71, 0, 0x1c000
	s_add_u32 s38, s40, 0xf0000
	s_addc_u32 s39, s41, 0
	s_add_i32 s70, s72, s81
	s_add_i32 s69, s70, 0x2000
	s_add_u32 s4, s42, 0x10080
	s_addc_u32 s5, s43, 0
	s_add_i32 s78, s71, s81
	s_add_i32 s77, s78, 0x2000
	v_lshl_add_u64 v[140:141], s[46:47], 0, v[128:129]
	ds_read_b128 v[180:183], v147
	ds_read_b128 v[184:187], v147 offset:1024
	ds_read_b128 v[188:191], v147 offset:2048
	ds_read_b128 v[192:195], v147 offset:3072
	ds_read_b128 v[196:199], v147 offset:4096
	ds_read_b128 v[200:203], v147 offset:5120
	ds_read_b128 v[204:207], v147 offset:6144
	ds_read_b128 v[210:213], v147 offset:7168
	global_load_lds_dwordx4 v[140:141], off
	v_lshl_add_u64 v[140:141], s[46:47], 0, v[132:133]
	s_mov_b32 m0, s79
	s_nop 0
	global_load_lds_dwordx4 v[140:141], off
	s_waitcnt vmcnt(8) lgkmcnt(0)
	s_setprio 1
	s_barrier
	v_mfma_f32_16x16x32_bf16 v[124:127], v[148:151], v[180:183], v[124:127]
	v_mfma_f32_16x16x32_bf16 v[120:123], v[156:159], v[180:183], v[120:123]
	v_mfma_f32_16x16x32_bf16 v[116:119], v[148:151], v[188:191], v[116:119]
	v_mfma_f32_16x16x32_bf16 v[108:111], v[156:159], v[188:191], v[108:111]
	v_mfma_f32_16x16x32_bf16 v[100:103], v[148:151], v[196:199], v[100:103]
	v_mfma_f32_16x16x32_bf16 v[92:95], v[156:159], v[196:199], v[92:95]
	v_mfma_f32_16x16x32_bf16 v[84:87], v[148:151], v[204:207], v[84:87]
	v_mfma_f32_16x16x32_bf16 v[76:79], v[156:159], v[204:207], v[76:79]
	v_mfma_f32_16x16x32_bf16 v[124:127], v[152:155], v[184:187], v[124:127]
	v_mfma_f32_16x16x32_bf16 v[120:123], v[160:163], v[184:187], v[120:123]
	v_mfma_f32_16x16x32_bf16 v[116:119], v[152:155], v[192:195], v[116:119]
	v_mfma_f32_16x16x32_bf16 v[108:111], v[160:163], v[192:195], v[108:111]
	v_mfma_f32_16x16x32_bf16 v[100:103], v[152:155], v[200:203], v[100:103]
	v_mfma_f32_16x16x32_bf16 v[92:95], v[160:163], v[200:203], v[92:95]
	v_mfma_f32_16x16x32_bf16 v[84:87], v[152:155], v[210:213], v[84:87]
	v_mfma_f32_16x16x32_bf16 v[76:79], v[160:163], v[210:213], v[76:79]
	s_setprio 0
	s_setprio 1
	v_mfma_f32_16x16x32_bf16 v[112:115], v[164:167], v[180:183], v[112:115]
	v_mfma_f32_16x16x32_bf16 v[104:107], v[172:175], v[180:183], v[104:107]
	v_mfma_f32_16x16x32_bf16 v[96:99], v[164:167], v[188:191], v[96:99]
	v_mfma_f32_16x16x32_bf16 v[88:91], v[172:175], v[188:191], v[88:91]
	v_mfma_f32_16x16x32_bf16 v[80:83], v[164:167], v[196:199], v[80:83]
	v_mfma_f32_16x16x32_bf16 v[72:75], v[172:175], v[196:199], v[72:75]
	v_mfma_f32_16x16x32_bf16 v[68:71], v[164:167], v[204:207], v[68:71]
	v_mfma_f32_16x16x32_bf16 v[64:67], v[172:175], v[204:207], v[64:67]
	v_mfma_f32_16x16x32_bf16 v[112:115], v[168:171], v[184:187], v[112:115]
	v_mfma_f32_16x16x32_bf16 v[104:107], v[176:179], v[184:187], v[104:107]
	v_mfma_f32_16x16x32_bf16 v[96:99], v[168:171], v[192:195], v[96:99]
	v_mfma_f32_16x16x32_bf16 v[88:91], v[176:179], v[192:195], v[88:91]
	v_mfma_f32_16x16x32_bf16 v[80:83], v[168:171], v[200:203], v[80:83]
	v_mfma_f32_16x16x32_bf16 v[72:75], v[176:179], v[200:203], v[72:75]
	v_mfma_f32_16x16x32_bf16 v[68:71], v[168:171], v[210:213], v[68:71]
	v_mfma_f32_16x16x32_bf16 v[64:67], v[176:179], v[210:213], v[64:67]
	s_setprio 0
	s_barrier
	s_mov_b32 m0, s76
	v_lshl_add_u64 v[140:141], s[42:43], 0, v[130:131]
	ds_read_b128 v[180:183], v147 offset:16384
	ds_read_b128 v[184:187], v147 offset:17408
	ds_read_b128 v[188:191], v147 offset:18432
	ds_read_b128 v[192:195], v147 offset:19456
	ds_read_b128 v[196:199], v147 offset:20480
	ds_read_b128 v[200:203], v147 offset:21504
	ds_read_b128 v[204:207], v147 offset:22528
	ds_read_b128 v[210:213], v147 offset:23552
	global_load_lds_dwordx4 v[140:141], off
	v_lshl_add_u64 v[214:215], s[42:43], 0, v[134:135]
	s_mov_b32 m0, s73
	v_lshl_add_u64 v[216:217], s[44:45], 0, v[130:131]
	global_load_lds_dwordx4 v[214:215], off
	s_mov_b32 m0, s75
	v_lshl_add_u64 v[218:219], s[40:41], 0, v[132:133]
	global_load_lds_dwordx4 v[216:217], off
	v_lshl_add_u64 v[216:217], s[44:45], 0, v[134:135]
	s_mov_b32 m0, s74
	s_nop 0
	global_load_lds_dwordx4 v[216:217], off
	v_lshl_add_u64 v[216:217], s[40:41], 0, v[128:129]
	s_mov_b32 m0, s49
	s_nop 0
	global_load_lds_dwordx4 v[216:217], off
	s_mov_b32 m0, s50
	s_nop 0
	global_load_lds_dwordx4 v[218:219], off
	s_waitcnt vmcnt(8) lgkmcnt(0)
	s_setprio 1
	s_barrier
; #define PG8_STAGE(bufoff, gbase, voff) do { _Pragma("unroll") for (int _i = 0; _i < 2; ++_i) \
;         __builtin_amdgcn_global_load_lds((const unsigned*)((const char*)(gbase) + (voff)[_i]), (LAS unsigned*)(lds + (bufoff) + ldsw + _i * 8192), 16, 0, 0); } while (0)
; #define PG8_LDA(dst, b, h) do { _Pragma("unroll") for (int m = 0; m < 4; ++m) _Pragma("unroll") for (int k = 0; k < 2; ++k) dst[m][k] = *(const LAS bf16x8*)(lds + PG8_SA(b, h) + aoff + m * 2048 + k * 1024); } while (0)
; #define PG8_LDB(dst, b, h) do { _Pragma("unroll") for (int n = 0; n < 2; ++n) _Pragma("unroll") for (int k = 0; k < 2; ++k) dst[n][k] = *(const LAS bf16x8*)(lds + PG8_SB(b, h) + boff + n * 2048 + k * 1024); } while (0)
; #define PG8_MMA(ai, bj, At, Bt) do { __builtin_amdgcn_s_setprio(1); _Pragma("unroll") for (int m = 0; m < 4; ++m) _Pragma("unroll") for (int n = 0; n < 2; ++n) _Pragma("unroll") for (int k = 0; k < 2; ++k) \
;         acc[ai][bj][m][n] = __builtin_amdgcn_mfma_f32_16x16x32_bf16(Bt[n][k], At[m][k], acc[ai][bj][m][n], 0, 0, 0); __builtin_amdgcn_s_setprio(0); } while (0)
; #define PG8_WAIT_V(n) asm volatile("s_waitcnt vmcnt(" #n ")" ::: "memory")
; #define PG8_WAIT_L(n) asm volatile("s_waitcnt lgkmcnt(" #n ")" ::: "memory")
; #define PG8_BAR __builtin_amdgcn_s_barrier()
; #define PG8_SCHED __builtin_amdgcn_sched_barrier(0)
; template <class Epi, class Sched>
; __device__ __forceinline__ void gemm_phase(LAS unsigned char* lds, const Gemm g, const Sched& S, const Epi& E, const int wave_s) {
;     ...
;             PG8_WAIT_V(8); PG8_WAIT_L(0); PG8_BAR; PG8_MMA(1, 0, At, B0); PG8_MMA(1, 1, At, B1); PG8_BAR; PG8_SCHED;
;             PG8_LDB(B0, 1, 0); PG8_LDB(B1, 1, 1); PG8_SCHED; PG8_LDA(At, 1, 0); PG8_STAGE(PG8_SA(0, 1), a2 + hstepA, voffA);
;             PG8_WAIT_V(8); PG8_WAIT_L(0); PG8_BAR; PG8_MMA(0, 0, At, B0); PG8_MMA(0, 1, At, B1); PG8_BAR; PG8_SCHED;
	v_mfma_f32_16x16x32_bf16 v[60:63], v[148:151], v[180:183], v[60:63]
	v_mfma_f32_16x16x32_bf16 v[56:59], v[156:159], v[180:183], v[56:59]
	v_mfma_f32_16x16x32_bf16 v[52:55], v[148:151], v[188:191], v[52:55]
	v_mfma_f32_16x16x32_bf16 v[44:47], v[156:159], v[188:191], v[44:47]
	v_mfma_f32_16x16x32_bf16 v[36:39], v[148:151], v[196:199], v[36:39]
	v_mfma_f32_16x16x32_bf16 v[28:31], v[156:159], v[196:199], v[28:31]
	v_mfma_f32_16x16x32_bf16 v[20:23], v[148:151], v[204:207], v[20:23]
	v_mfma_f32_16x16x32_bf16 v[12:15], v[156:159], v[204:207], v[12:15]
	v_mfma_f32_16x16x32_bf16 v[60:63], v[152:155], v[184:187], v[60:63]
	v_mfma_f32_16x16x32_bf16 v[56:59], v[160:163], v[184:187], v[56:59]
	v_mfma_f32_16x16x32_bf16 v[52:55], v[152:155], v[192:195], v[52:55]
	v_mfma_f32_16x16x32_bf16 v[44:47], v[160:163], v[192:195], v[44:47]
	v_mfma_f32_16x16x32_bf16 v[36:39], v[152:155], v[200:203], v[36:39]
	v_mfma_f32_16x16x32_bf16 v[28:31], v[160:163], v[200:203], v[28:31]
	v_mfma_f32_16x16x32_bf16 v[20:23], v[152:155], v[210:213], v[20:23]
	v_mfma_f32_16x16x32_bf16 v[12:15], v[160:163], v[210:213], v[12:15]
	s_setprio 0
	s_setprio 1
	v_mfma_f32_16x16x32_bf16 v[48:51], v[164:167], v[180:183], v[48:51]
	v_mfma_f32_16x16x32_bf16 v[40:43], v[172:175], v[180:183], v[40:43]
	v_mfma_f32_16x16x32_bf16 v[32:35], v[164:167], v[188:191], v[32:35]
	v_mfma_f32_16x16x32_bf16 v[24:27], v[172:175], v[188:191], v[24:27]
	v_mfma_f32_16x16x32_bf16 v[16:19], v[164:167], v[196:199], v[16:19]
	v_mfma_f32_16x16x32_bf16 v[8:11], v[172:175], v[196:199], v[8:11]
	v_mfma_f32_16x16x32_bf16 v[4:7], v[164:167], v[204:207], v[4:7]
	v_mfma_f32_16x16x32_bf16 v[0:3], v[172:175], v[204:207], v[0:3]
	v_mfma_f32_16x16x32_bf16 v[48:51], v[168:171], v[184:187], v[48:51]
	v_mfma_f32_16x16x32_bf16 v[40:43], v[176:179], v[184:187], v[40:43]
	v_mfma_f32_16x16x32_bf16 v[32:35], v[168:171], v[192:195], v[32:35]
	v_mfma_f32_16x16x32_bf16 v[24:27], v[176:179], v[192:195], v[24:27]
	v_mfma_f32_16x16x32_bf16 v[16:19], v[168:171], v[200:203], v[16:19]
	v_mfma_f32_16x16x32_bf16 v[8:11], v[176:179], v[200:203], v[8:11]
	v_mfma_f32_16x16x32_bf16 v[4:7], v[168:171], v[210:213], v[4:7]
	v_mfma_f32_16x16x32_bf16 v[0:3], v[176:179], v[210:213], v[0:3]
	s_setprio 0
	s_barrier
	v_add_u32_e32 v160, s72, v143
	v_add_u32_e32 v176, s71, v143
	ds_read_b128 v[148:151], v160
	ds_read_b128 v[152:155], v160 offset:1024
	ds_read_b128 v[156:159], v160 offset:2048
	ds_read_b128 v[160:163], v160 offset:3072
	ds_read_b128 v[164:167], v176
	ds_read_b128 v[168:171], v176 offset:1024
	ds_read_b128 v[172:175], v176 offset:2048
	ds_read_b128 v[176:179], v176 offset:3072
	s_mov_b32 m0, s51
	v_lshl_add_u64 v[220:221], s[38:39], 0, v[128:129]
	ds_read_b128 v[180:183], v147 offset:32768
	ds_read_b128 v[184:187], v147 offset:33792
	ds_read_b128 v[188:191], v147 offset:34816
	ds_read_b128 v[192:195], v147 offset:35840
	ds_read_b128 v[196:199], v147 offset:36864
	ds_read_b128 v[200:203], v147 offset:37888
	ds_read_b128 v[204:207], v147 offset:38912
	ds_read_b128 v[210:213], v147 offset:39936
	global_load_lds_dwordx4 v[220:221], off
	v_lshl_add_u64 v[220:221], s[38:39], 0, v[132:133]
	s_mov_b32 m0, s52
	s_nop 0
	global_load_lds_dwordx4 v[220:221], off
	s_waitcnt vmcnt(8) lgkmcnt(0)
	s_setprio 1
	s_barrier
	v_mfma_f32_16x16x32_bf16 v[124:127], v[148:151], v[180:183], v[124:127]
	v_mfma_f32_16x16x32_bf16 v[120:123], v[156:159], v[180:183], v[120:123]
	v_mfma_f32_16x16x32_bf16 v[116:119], v[148:151], v[188:191], v[116:119]
	v_mfma_f32_16x16x32_bf16 v[108:111], v[156:159], v[188:191], v[108:111]
	v_mfma_f32_16x16x32_bf16 v[100:103], v[148:151], v[196:199], v[100:103]
	v_mfma_f32_16x16x32_bf16 v[92:95], v[156:159], v[196:199], v[92:95]
	v_mfma_f32_16x16x32_bf16 v[84:87], v[148:151], v[204:207], v[84:87]
	v_mfma_f32_16x16x32_bf16 v[76:79], v[156:159], v[204:207], v[76:79]
	v_mfma_f32_16x16x32_bf16 v[124:127], v[152:155], v[184:187], v[124:127]
	v_mfma_f32_16x16x32_bf16 v[120:123], v[160:163], v[184:187], v[120:123]
	v_mfma_f32_16x16x32_bf16 v[116:119], v[152:155], v[192:195], v[116:119]
	v_mfma_f32_16x16x32_bf16 v[108:111], v[160:163], v[192:195], v[108:111]
	v_mfma_f32_16x16x32_bf16 v[100:103], v[152:155], v[200:203], v[100:103]
	v_mfma_f32_16x16x32_bf16 v[92:95], v[160:163], v[200:203], v[92:95]
	v_mfma_f32_16x16x32_bf16 v[84:87], v[152:155], v[210:213], v[84:87]
	v_mfma_f32_16x16x32_bf16 v[76:79], v[160:163], v[210:213], v[76:79]
	s_setprio 0
	s_setprio 1
	v_mfma_f32_16x16x32_bf16 v[112:115], v[164:167], v[180:183], v[112:115]
	v_mfma_f32_16x16x32_bf16 v[104:107], v[172:175], v[180:183], v[104:107]
	v_mfma_f32_16x16x32_bf16 v[96:99], v[164:167], v[188:191], v[96:99]
	v_mfma_f32_16x16x32_bf16 v[88:91], v[172:175], v[188:191], v[88:91]
	v_mfma_f32_16x16x32_bf16 v[80:83], v[164:167], v[196:199], v[80:83]
	v_mfma_f32_16x16x32_bf16 v[72:75], v[172:175], v[196:199], v[72:75]
	v_mfma_f32_16x16x32_bf16 v[68:71], v[164:167], v[204:207], v[68:71]
	v_mfma_f32_16x16x32_bf16 v[64:67], v[172:175], v[204:207], v[64:67]
	v_mfma_f32_16x16x32_bf16 v[112:115], v[168:171], v[184:187], v[112:115]
	v_mfma_f32_16x16x32_bf16 v[104:107], v[176:179], v[184:187], v[104:107]
	v_mfma_f32_16x16x32_bf16 v[96:99], v[168:171], v[192:195], v[96:99]
	v_mfma_f32_16x16x32_bf16 v[88:91], v[176:179], v[192:195], v[88:91]
	v_mfma_f32_16x16x32_bf16 v[80:83], v[168:171], v[200:203], v[80:83]
	v_mfma_f32_16x16x32_bf16 v[72:75], v[176:179], v[200:203], v[72:75]
	v_mfma_f32_16x16x32_bf16 v[68:71], v[168:171], v[210:213], v[68:71]
	v_mfma_f32_16x16x32_bf16 v[64:67], v[176:179], v[210:213], v[64:67]
	s_setprio 0
	s_barrier
; #define PG8_STAGE(bufoff, gbase, voff) do { _Pragma("unroll") for (int _i = 0; _i < 2; ++_i) \
;         __builtin_amdgcn_global_load_lds((const unsigned*)((const char*)(gbase) + (voff)[_i]), (LAS unsigned*)(lds + (bufoff) + ldsw + _i * 8192), 16, 0, 0); } while (0)
; #define PG8_LDA(dst, b, h) do { _Pragma("unroll") for (int m = 0; m < 4; ++m) _Pragma("unroll") for (int k = 0; k < 2; ++k) dst[m][k] = *(const LAS bf16x8*)(lds + PG8_SA(b, h) + aoff + m * 2048 + k * 1024); } while (0)
; #define PG8_MMA(ai, bj, At, Bt) do { __builtin_amdgcn_s_setprio(1); _Pragma("unroll") for (int m = 0; m < 4; ++m) _Pragma("unroll") for (int n = 0; n < 2; ++n) _Pragma("unroll") for (int k = 0; k < 2; ++k) \
;         acc[ai][bj][m][n] = __builtin_amdgcn_mfma_f32_16x16x32_bf16(Bt[n][k], At[m][k], acc[ai][bj][m][n], 0, 0, 0); __builtin_amdgcn_s_setprio(0); } while (0)
; #define PG8_WAIT_V(n) asm volatile("s_waitcnt vmcnt(" #n ")" ::: "memory")
; #define PG8_WAIT_L(n) asm volatile("s_waitcnt lgkmcnt(" #n ")" ::: "memory")
; #define PG8_BAR __builtin_amdgcn_s_barrier()
; #define PG8_SCHED __builtin_amdgcn_sched_barrier(0)
; template <class Epi, class Sched>
; __device__ __forceinline__ void gemm_phase(LAS unsigned char* lds, const Gemm g, const Sched& S, const Epi& E, const int wave_s) {
;     ...
;             PG8_LDA(At, 1, 1); PG8_STAGE(PG8_SB(1, 0), b3, voffB); PG8_STAGE(PG8_SB(1, 1), b3 + hstepB, voffB); PG8_STAGE(PG8_SA(1, 0), a3, voffA);
;             PG8_WAIT_V(8); PG8_WAIT_L(0); PG8_BAR; PG8_MMA(1, 0, At, B0); PG8_MMA(1, 1, At, B1); PG8_BAR; PG8_SCHED;
;         }
;         if (wr == 0) PG8_BAR;
	s_mov_b32 m0, s70
	v_lshl_add_u64 v[140:141], v[140:141], 0, s[14:15]
	ds_read_b128 v[180:183], v147 offset:49152
	ds_read_b128 v[184:187], v147 offset:50176
	ds_read_b128 v[188:191], v147 offset:51200
	ds_read_b128 v[192:195], v147 offset:52224
	ds_read_b128 v[196:199], v147 offset:53248
	ds_read_b128 v[200:203], v147 offset:54272
	ds_read_b128 v[204:207], v147 offset:55296
	ds_read_b128 v[210:213], v147 offset:56320
	global_load_lds_dwordx4 v[140:141], off
	v_lshl_add_u64 v[140:141], v[214:215], 0, s[14:15]
	s_mov_b32 m0, s69
	s_nop 0
	global_load_lds_dwordx4 v[140:141], off
	v_lshl_add_u64 v[140:141], s[4:5], 0, v[130:131]
	s_mov_b32 m0, s78
	s_nop 0
	global_load_lds_dwordx4 v[140:141], off
	v_lshl_add_u64 v[140:141], s[4:5], 0, v[134:135]
	s_mov_b32 m0, s77
	s_nop 0
	global_load_lds_dwordx4 v[140:141], off
	v_lshl_add_u64 v[140:141], v[216:217], 0, s[14:15]
	s_mov_b32 m0, s54
	s_nop 0
	global_load_lds_dwordx4 v[140:141], off
	v_lshl_add_u64 v[140:141], v[218:219], 0, s[14:15]
	s_mov_b32 m0, s55
	s_nop 0
	global_load_lds_dwordx4 v[140:141], off
	s_waitcnt vmcnt(8) lgkmcnt(0)
	s_setprio 1
	s_barrier
	v_mfma_f32_16x16x32_bf16 v[60:63], v[148:151], v[180:183], v[60:63]
	v_mfma_f32_16x16x32_bf16 v[56:59], v[156:159], v[180:183], v[56:59]
	v_mfma_f32_16x16x32_bf16 v[52:55], v[148:151], v[188:191], v[52:55]
	v_mfma_f32_16x16x32_bf16 v[44:47], v[156:159], v[188:191], v[44:47]
	v_mfma_f32_16x16x32_bf16 v[36:39], v[148:151], v[196:199], v[36:39]
	v_mfma_f32_16x16x32_bf16 v[28:31], v[156:159], v[196:199], v[28:31]
	v_mfma_f32_16x16x32_bf16 v[20:23], v[148:151], v[204:207], v[20:23]
	v_mfma_f32_16x16x32_bf16 v[12:15], v[156:159], v[204:207], v[12:15]
	v_mfma_f32_16x16x32_bf16 v[60:63], v[152:155], v[184:187], v[60:63]
	v_mfma_f32_16x16x32_bf16 v[56:59], v[160:163], v[184:187], v[56:59]
	v_mfma_f32_16x16x32_bf16 v[52:55], v[152:155], v[192:195], v[52:55]
	v_mfma_f32_16x16x32_bf16 v[44:47], v[160:163], v[192:195], v[44:47]
	v_mfma_f32_16x16x32_bf16 v[36:39], v[152:155], v[200:203], v[36:39]
	v_mfma_f32_16x16x32_bf16 v[28:31], v[160:163], v[200:203], v[28:31]
	v_mfma_f32_16x16x32_bf16 v[20:23], v[152:155], v[210:213], v[20:23]
	v_mfma_f32_16x16x32_bf16 v[12:15], v[160:163], v[210:213], v[12:15]
	s_setprio 0
	s_setprio 1
	v_mfma_f32_16x16x32_bf16 v[48:51], v[164:167], v[180:183], v[48:51]
	v_mfma_f32_16x16x32_bf16 v[40:43], v[172:175], v[180:183], v[40:43]
	v_mfma_f32_16x16x32_bf16 v[32:35], v[164:167], v[188:191], v[32:35]
	v_mfma_f32_16x16x32_bf16 v[24:27], v[172:175], v[188:191], v[24:27]
	v_mfma_f32_16x16x32_bf16 v[16:19], v[164:167], v[196:199], v[16:19]
	v_mfma_f32_16x16x32_bf16 v[8:11], v[172:175], v[196:199], v[8:11]
	v_mfma_f32_16x16x32_bf16 v[4:7], v[164:167], v[204:207], v[4:7]
	v_mfma_f32_16x16x32_bf16 v[0:3], v[172:175], v[204:207], v[0:3]
	v_mfma_f32_16x16x32_bf16 v[48:51], v[168:171], v[184:187], v[48:51]
	v_mfma_f32_16x16x32_bf16 v[40:43], v[176:179], v[184:187], v[40:43]
	v_mfma_f32_16x16x32_bf16 v[32:35], v[168:171], v[192:195], v[32:35]
	v_mfma_f32_16x16x32_bf16 v[24:27], v[176:179], v[192:195], v[24:27]
	v_mfma_f32_16x16x32_bf16 v[16:19], v[168:171], v[200:203], v[16:19]
	v_mfma_f32_16x16x32_bf16 v[8:11], v[176:179], v[200:203], v[8:11]
	v_mfma_f32_16x16x32_bf16 v[4:7], v[168:171], v[210:213], v[4:7]
	v_mfma_f32_16x16x32_bf16 v[0:3], v[176:179], v[210:213], v[0:3]
	s_setprio 0
	s_barrier
	s_movk_i32 s38, 0x100
	s_andn2_b64 vcc, exec, s[8:9]
	s_mov_b64 s[4:5], -1
	s_mov_b64 s[8:9], 0
	s_cbranch_vccz .LBB0_417
	s_and_b64 vcc, exec, s[16:17]
	s_cbranch_vccz .LBB0_420
	s_barrier

; #define PG8_STAGE(bufoff, gbase, voff) do { _Pragma("unroll") for (int _i = 0; _i < 2; ++_i) \
;         __builtin_amdgcn_global_load_lds((const unsigned*)((const char*)(gbase) + (voff)[_i]), (LAS unsigned*)(lds + (bufoff) + ldsw + _i * 8192), 16, 0, 0); } while (0)
; #define PG8_LDA(dst, b, h) do { _Pragma("unroll") for (int m = 0; m < 4; ++m) _Pragma("unroll") for (int k = 0; k < 2; ++k) dst[m][k] = *(const LAS bf16x8*)(lds + PG8_SA(b, h) + aoff + m * 2048 + k * 1024); } while (0)
; #define PG8_LDB(dst, b, h) do { _Pragma("unroll") for (int n = 0; n < 2; ++n) _Pragma("unroll") for (int k = 0; k < 2; ++k) dst[n][k] = *(const LAS bf16x8*)(lds + PG8_SB(b, h) + boff + n * 2048 + k * 1024); } while (0)
; #define PG8_MMA(ai, bj, At, Bt) do { __builtin_amdgcn_s_setprio(1); _Pragma("unroll") for (int m = 0; m < 4; ++m) _Pragma("unroll") for (int n = 0; n < 2; ++n) _Pragma("unroll") for (int k = 0; k < 2; ++k) \
;         acc[ai][bj][m][n] = __builtin_amdgcn_mfma_f32_16x16x32_bf16(Bt[n][k], At[m][k], acc[ai][bj][m][n], 0, 0, 0); __builtin_amdgcn_s_setprio(0); } while (0)
; #define PG8_WAIT_V(n) asm volatile("s_waitcnt vmcnt(" #n ")" ::: "memory")
; #define PG8_WAIT_L(n) asm volatile("s_waitcnt lgkmcnt(" #n ")" ::: "memory")
; #define PG8_BAR __builtin_amdgcn_s_barrier()
; #define PG8_SCHED __builtin_amdgcn_sched_barrier(0)
; template <class Epi, class Sched>
; __device__ __forceinline__ void gemm_phase(LAS unsigned char* lds, const Gemm g, const Sched& S, const Epi& E, const int wave_s) {
;     ...
;             const bool last = (t == nt - 2);
;             const char* a1 = cA + (size_t)(t + 1) * kstep;
;             const char* a2 = last ? nA : cA + (size_t)(t + 2) * kstep; const char* b2 = last ? nB : cB + (size_t)(t + 2) * kstep;
;             const char* a3 = a2 + kstep; const char* b3 = b2 + kstep;
;             PG8_LDB(B0, 0, 0); PG8_LDB(B1, 0, 1); PG8_SCHED; PG8_LDA(At, 0, 0); PG8_STAGE(PG8_SA(1, 1), a1 + hstepA, voffA);
;             PG8_WAIT_V(8); PG8_WAIT_L(0); PG8_BAR; PG8_MMA(0, 0, At, B0); PG8_MMA(0, 1, At, B1); PG8_BAR; PG8_SCHED;
;             PG8_LDA(At, 0, 1); PG8_STAGE(PG8_SB(0, 0), b2, voffB); PG8_STAGE(PG8_SB(0, 1), b2 + hstepB, voffB); PG8_STAGE(PG8_SA(0, 0), a2, voffA);
.LBB0_860:
	ds_read_b128 v[100:103], v212
	ds_read_b128 v[108:111], v212 offset:1024
	ds_read_b128 v[136:139], v212 offset:2048
	ds_read_b128 v[140:143], v212 offset:3072
	ds_read_b128 v[144:147], v213
	ds_read_b128 v[148:151], v213 offset:1024
	ds_read_b128 v[152:155], v213 offset:2048
	ds_read_b128 v[156:159], v213 offset:3072
	s_add_u32 s4, s40, 0xfffc0080
	s_addc_u32 s5, s41, -1
	s_cmp_eq_u32 s54, 12
	s_cselect_b32 s43, s9, s5
	s_cselect_b32 s42, s27, s4
	s_cselect_b32 s5, s29, s53
	s_cselect_b32 s4, s31, s39
	v_lshl_add_u64 v[206:207], s[40:41], 0, v[178:179]
	s_add_i32 m0, s3, 0xc000
	ds_read_b128 v[160:163], v214
	ds_read_b128 v[164:167], v214 offset:1024
	ds_read_b128 v[186:189], v214 offset:2048
	ds_read_b128 v[190:193], v214 offset:3072
	ds_read_b128 v[194:197], v214 offset:4096
	ds_read_b128 v[198:201], v214 offset:5120
	ds_read_b128 v[202:205], v214 offset:6144
	ds_read_b128 v[216:219], v214 offset:7168
	global_load_lds_dwordx4 v[206:207], off
	v_lshl_add_u64 v[206:207], s[40:41], 0, v[180:181]
	s_add_i32 m0, s3, 0xe000
	s_nop 0
	global_load_lds_dwordx4 v[206:207], off
	s_waitcnt vmcnt(8) lgkmcnt(0)
	s_setprio 1
	s_barrier
	v_mfma_f32_16x16x32_bf16 v[132:135], v[100:103], v[160:163], v[132:135]
	v_mfma_f32_16x16x32_bf16 v[128:131], v[136:139], v[160:163], v[128:131]
	v_mfma_f32_16x16x32_bf16 v[124:127], v[100:103], v[186:189], v[124:127]
	v_mfma_f32_16x16x32_bf16 v[120:123], v[136:139], v[186:189], v[120:123]
	v_mfma_f32_16x16x32_bf16 v[116:119], v[100:103], v[194:197], v[116:119]
	v_mfma_f32_16x16x32_bf16 v[112:115], v[136:139], v[194:197], v[112:115]
	v_mfma_f32_16x16x32_bf16 v[104:107], v[100:103], v[202:205], v[104:107]
	v_mfma_f32_16x16x32_bf16 v[96:99], v[136:139], v[202:205], v[96:99]
	v_mfma_f32_16x16x32_bf16 v[132:135], v[108:111], v[164:167], v[132:135]
	v_mfma_f32_16x16x32_bf16 v[128:131], v[140:143], v[164:167], v[128:131]
	v_mfma_f32_16x16x32_bf16 v[124:127], v[108:111], v[190:193], v[124:127]
	v_mfma_f32_16x16x32_bf16 v[120:123], v[140:143], v[190:193], v[120:123]
	v_mfma_f32_16x16x32_bf16 v[116:119], v[108:111], v[198:201], v[116:119]
	v_mfma_f32_16x16x32_bf16 v[112:115], v[140:143], v[198:201], v[112:115]
	v_mfma_f32_16x16x32_bf16 v[104:107], v[108:111], v[216:219], v[104:107]
	v_mfma_f32_16x16x32_bf16 v[96:99], v[140:143], v[216:219], v[96:99]
	s_setprio 0
	s_setprio 1
	v_mfma_f32_16x16x32_bf16 v[60:63], v[144:147], v[160:163], v[60:63]
	v_mfma_f32_16x16x32_bf16 v[56:59], v[152:155], v[160:163], v[56:59]
	v_mfma_f32_16x16x32_bf16 v[52:55], v[144:147], v[186:189], v[52:55]
	v_mfma_f32_16x16x32_bf16 v[48:51], v[152:155], v[186:189], v[48:51]
	v_mfma_f32_16x16x32_bf16 v[44:47], v[144:147], v[194:197], v[44:47]
	v_mfma_f32_16x16x32_bf16 v[40:43], v[152:155], v[194:197], v[40:43]
	v_mfma_f32_16x16x32_bf16 v[36:39], v[144:147], v[202:205], v[36:39]
	v_mfma_f32_16x16x32_bf16 v[32:35], v[152:155], v[202:205], v[32:35]
	v_mfma_f32_16x16x32_bf16 v[60:63], v[148:151], v[164:167], v[60:63]
	v_mfma_f32_16x16x32_bf16 v[56:59], v[156:159], v[164:167], v[56:59]
	v_mfma_f32_16x16x32_bf16 v[52:55], v[148:151], v[190:193], v[52:55]
	v_mfma_f32_16x16x32_bf16 v[48:51], v[156:159], v[190:193], v[48:51]
	v_mfma_f32_16x16x32_bf16 v[44:47], v[148:151], v[198:201], v[44:47]
	v_mfma_f32_16x16x32_bf16 v[40:43], v[156:159], v[198:201], v[40:43]
	v_mfma_f32_16x16x32_bf16 v[36:39], v[148:151], v[216:219], v[36:39]
	v_mfma_f32_16x16x32_bf16 v[32:35], v[156:159], v[216:219], v[32:35]
	s_setprio 0
	s_barrier
	s_add_i32 s55, s50, s81
	v_lshl_add_u64 v[206:207], s[4:5], 0, v[170:171]
	s_mov_b32 m0, s55
	ds_read_b128 v[160:163], v214 offset:16384
	ds_read_b128 v[164:167], v214 offset:17408
	ds_read_b128 v[186:189], v214 offset:18432
	ds_read_b128 v[190:193], v214 offset:19456
	ds_read_b128 v[194:197], v214 offset:20480
	ds_read_b128 v[198:201], v214 offset:21504
	ds_read_b128 v[202:205], v214 offset:22528
	ds_read_b128 v[216:219], v214 offset:23552
	global_load_lds_dwordx4 v[206:207], off
	s_add_i32 m0, s55, 0x2000
	s_add_u32 s56, s4, 0x40000
	v_lshl_add_u64 v[220:221], s[4:5], 0, v[174:175]
	s_addc_u32 s57, s5, 0
	s_add_i32 s55, s51, s81
	global_load_lds_dwordx4 v[220:221], off
	v_lshl_add_u64 v[222:223], s[56:57], 0, v[170:171]
	s_mov_b32 m0, s55
	v_lshl_add_u64 v[224:225], s[42:43], 0, v[172:173]
	global_load_lds_dwordx4 v[222:223], off
	v_lshl_add_u64 v[222:223], s[56:57], 0, v[174:175]
	s_add_i32 m0, s55, 0x2000
	s_nop 0
	global_load_lds_dwordx4 v[222:223], off
	v_lshl_add_u64 v[222:223], s[42:43], 0, v[168:169]
	s_mov_b32 m0, s3
	s_nop 0
	global_load_lds_dwordx4 v[222:223], off
	s_mov_b32 m0, s33
	s_nop 0
	global_load_lds_dwordx4 v[224:225], off
	s_waitcnt vmcnt(8) lgkmcnt(0)
	s_setprio 1
	s_barrier
; #define PG8_STAGE(bufoff, gbase, voff) do { _Pragma("unroll") for (int _i = 0; _i < 2; ++_i) \
;         __builtin_amdgcn_global_load_lds((const unsigned*)((const char*)(gbase) + (voff)[_i]), (LAS unsigned*)(lds + (bufoff) + ldsw + _i * 8192), 16, 0, 0); } while (0)
; #define PG8_LDA(dst, b, h) do { _Pragma("unroll") for (int m = 0; m < 4; ++m) _Pragma("unroll") for (int k = 0; k < 2; ++k) dst[m][k] = *(const LAS bf16x8*)(lds + PG8_SA(b, h) + aoff + m * 2048 + k * 1024); } while (0)
; #define PG8_LDB(dst, b, h) do { _Pragma("unroll") for (int n = 0; n < 2; ++n) _Pragma("unroll") for (int k = 0; k < 2; ++k) dst[n][k] = *(const LAS bf16x8*)(lds + PG8_SB(b, h) + boff + n * 2048 + k * 1024); } while (0)
; #define PG8_MMA(ai, bj, At, Bt) do { __builtin_amdgcn_s_setprio(1); _Pragma("unroll") for (int m = 0; m < 4; ++m) _Pragma("unroll") for (int n = 0; n < 2; ++n) _Pragma("unroll") for (int k = 0; k < 2; ++k) \
;         acc[ai][bj][m][n] = __builtin_amdgcn_mfma_f32_16x16x32_bf16(Bt[n][k], At[m][k], acc[ai][bj][m][n], 0, 0, 0); __builtin_amdgcn_s_setprio(0); } while (0)
; #define PG8_WAIT_V(n) asm volatile("s_waitcnt vmcnt(" #n ")" ::: "memory")
; #define PG8_WAIT_L(n) asm volatile("s_waitcnt lgkmcnt(" #n ")" ::: "memory")
; #define PG8_BAR __builtin_amdgcn_s_barrier()
; #define PG8_SCHED __builtin_amdgcn_sched_barrier(0)
; template <class Epi, class Sched>
; __device__ __forceinline__ void gemm_phase(LAS unsigned char* lds, const Gemm g, const Sched& S, const Epi& E, const int wave_s) {
;     ...
;             PG8_WAIT_V(8); PG8_WAIT_L(0); PG8_BAR; PG8_MMA(1, 0, At, B0); PG8_MMA(1, 1, At, B1); PG8_BAR; PG8_SCHED;
;             PG8_LDB(B0, 1, 0); PG8_LDB(B1, 1, 1); PG8_SCHED; PG8_LDA(At, 1, 0); PG8_STAGE(PG8_SA(0, 1), a2 + hstepA, voffA);
;             PG8_WAIT_V(8); PG8_WAIT_L(0); PG8_BAR; PG8_MMA(0, 0, At, B0); PG8_MMA(0, 1, At, B1); PG8_BAR; PG8_SCHED;
	v_mfma_f32_16x16x32_bf16 v[92:95], v[100:103], v[160:163], v[92:95]
	v_mfma_f32_16x16x32_bf16 v[88:91], v[136:139], v[160:163], v[88:91]
	v_mfma_f32_16x16x32_bf16 v[84:87], v[100:103], v[186:189], v[84:87]
	v_mfma_f32_16x16x32_bf16 v[80:83], v[136:139], v[186:189], v[80:83]
	v_mfma_f32_16x16x32_bf16 v[76:79], v[100:103], v[194:197], v[76:79]
	v_mfma_f32_16x16x32_bf16 v[72:75], v[136:139], v[194:197], v[72:75]
	v_mfma_f32_16x16x32_bf16 v[68:71], v[100:103], v[202:205], v[68:71]
	v_mfma_f32_16x16x32_bf16 v[64:67], v[136:139], v[202:205], v[64:67]
	v_mfma_f32_16x16x32_bf16 v[92:95], v[108:111], v[164:167], v[92:95]
	v_mfma_f32_16x16x32_bf16 v[88:91], v[140:143], v[164:167], v[88:91]
	v_mfma_f32_16x16x32_bf16 v[84:87], v[108:111], v[190:193], v[84:87]
	v_mfma_f32_16x16x32_bf16 v[80:83], v[140:143], v[190:193], v[80:83]
	v_mfma_f32_16x16x32_bf16 v[76:79], v[108:111], v[198:201], v[76:79]
	v_mfma_f32_16x16x32_bf16 v[72:75], v[140:143], v[198:201], v[72:75]
	v_mfma_f32_16x16x32_bf16 v[68:71], v[108:111], v[216:219], v[68:71]
	v_mfma_f32_16x16x32_bf16 v[64:67], v[140:143], v[216:219], v[64:67]
	s_setprio 0
	s_setprio 1
	v_mfma_f32_16x16x32_bf16 v[28:31], v[144:147], v[160:163], v[28:31]
	v_mfma_f32_16x16x32_bf16 v[24:27], v[152:155], v[160:163], v[24:27]
	v_mfma_f32_16x16x32_bf16 v[20:23], v[144:147], v[186:189], v[20:23]
	v_mfma_f32_16x16x32_bf16 v[16:19], v[152:155], v[186:189], v[16:19]
	v_mfma_f32_16x16x32_bf16 v[12:15], v[144:147], v[194:197], v[12:15]
	v_mfma_f32_16x16x32_bf16 v[8:11], v[152:155], v[194:197], v[8:11]
	v_mfma_f32_16x16x32_bf16 v[4:7], v[144:147], v[202:205], v[4:7]
	v_mfma_f32_16x16x32_bf16 v[0:3], v[152:155], v[202:205], v[0:3]
	v_mfma_f32_16x16x32_bf16 v[28:31], v[148:151], v[164:167], v[28:31]
	v_mfma_f32_16x16x32_bf16 v[24:27], v[156:159], v[164:167], v[24:27]
	v_mfma_f32_16x16x32_bf16 v[20:23], v[148:151], v[190:193], v[20:23]
	v_mfma_f32_16x16x32_bf16 v[16:19], v[156:159], v[190:193], v[16:19]
	v_mfma_f32_16x16x32_bf16 v[12:15], v[148:151], v[198:201], v[12:15]
	v_mfma_f32_16x16x32_bf16 v[8:11], v[156:159], v[198:201], v[8:11]
	v_mfma_f32_16x16x32_bf16 v[4:7], v[148:151], v[216:219], v[4:7]
	v_mfma_f32_16x16x32_bf16 v[0:3], v[156:159], v[216:219], v[0:3]
	s_setprio 0
	s_barrier
	s_add_i32 s55, 0, 0x18000
	s_add_i32 s56, 0, 0x1c000
	v_add_u32_e32 v140, s55, v210
	v_add_u32_e32 v156, s56, v210
	ds_read_b128 v[100:103], v140
	ds_read_b128 v[108:111], v140 offset:1024
	ds_read_b128 v[136:139], v140 offset:2048
	ds_read_b128 v[140:143], v140 offset:3072
	ds_read_b128 v[144:147], v156
	ds_read_b128 v[148:151], v156 offset:1024
	ds_read_b128 v[152:155], v156 offset:2048
	ds_read_b128 v[156:159], v156 offset:3072
	s_add_u32 s42, s42, 0x40000
	s_addc_u32 s43, s43, 0
	s_mov_b32 m0, s44
	v_lshl_add_u64 v[226:227], s[42:43], 0, v[168:169]
	ds_read_b128 v[160:163], v214 offset:32768
	ds_read_b128 v[164:167], v214 offset:33792
	ds_read_b128 v[186:189], v214 offset:34816
	ds_read_b128 v[190:193], v214 offset:35840
	ds_read_b128 v[194:197], v214 offset:36864
	ds_read_b128 v[198:201], v214 offset:37888
	ds_read_b128 v[202:205], v214 offset:38912
	ds_read_b128 v[216:219], v214 offset:39936
	global_load_lds_dwordx4 v[226:227], off
	v_lshl_add_u64 v[226:227], s[42:43], 0, v[172:173]
	s_mov_b32 m0, s45
	s_nop 0
	global_load_lds_dwordx4 v[226:227], off
	s_waitcnt vmcnt(8) lgkmcnt(0)
	s_setprio 1
	s_barrier
	v_mfma_f32_16x16x32_bf16 v[132:135], v[100:103], v[160:163], v[132:135]
	v_mfma_f32_16x16x32_bf16 v[128:131], v[136:139], v[160:163], v[128:131]
	v_mfma_f32_16x16x32_bf16 v[124:127], v[100:103], v[186:189], v[124:127]
	v_mfma_f32_16x16x32_bf16 v[120:123], v[136:139], v[186:189], v[120:123]
	v_mfma_f32_16x16x32_bf16 v[116:119], v[100:103], v[194:197], v[116:119]
	v_mfma_f32_16x16x32_bf16 v[112:115], v[136:139], v[194:197], v[112:115]
	v_mfma_f32_16x16x32_bf16 v[104:107], v[100:103], v[202:205], v[104:107]
	v_mfma_f32_16x16x32_bf16 v[96:99], v[136:139], v[202:205], v[96:99]
	v_mfma_f32_16x16x32_bf16 v[132:135], v[108:111], v[164:167], v[132:135]
	v_mfma_f32_16x16x32_bf16 v[128:131], v[140:143], v[164:167], v[128:131]
	v_mfma_f32_16x16x32_bf16 v[124:127], v[108:111], v[190:193], v[124:127]
	v_mfma_f32_16x16x32_bf16 v[120:123], v[140:143], v[190:193], v[120:123]
	v_mfma_f32_16x16x32_bf16 v[116:119], v[108:111], v[198:201], v[116:119]
	v_mfma_f32_16x16x32_bf16 v[112:115], v[140:143], v[198:201], v[112:115]
	v_mfma_f32_16x16x32_bf16 v[104:107], v[108:111], v[216:219], v[104:107]
	v_mfma_f32_16x16x32_bf16 v[96:99], v[140:143], v[216:219], v[96:99]
	s_setprio 0
	s_setprio 1
	v_mfma_f32_16x16x32_bf16 v[60:63], v[144:147], v[160:163], v[60:63]
	v_mfma_f32_16x16x32_bf16 v[56:59], v[152:155], v[160:163], v[56:59]
	v_mfma_f32_16x16x32_bf16 v[52:55], v[144:147], v[186:189], v[52:55]
	v_mfma_f32_16x16x32_bf16 v[48:51], v[152:155], v[186:189], v[48:51]
	v_mfma_f32_16x16x32_bf16 v[44:47], v[144:147], v[194:197], v[44:47]
	v_mfma_f32_16x16x32_bf16 v[40:43], v[152:155], v[194:197], v[40:43]
	v_mfma_f32_16x16x32_bf16 v[36:39], v[144:147], v[202:205], v[36:39]
	v_mfma_f32_16x16x32_bf16 v[32:35], v[152:155], v[202:205], v[32:35]
	v_mfma_f32_16x16x32_bf16 v[60:63], v[148:151], v[164:167], v[60:63]
	v_mfma_f32_16x16x32_bf16 v[56:59], v[156:159], v[164:167], v[56:59]
	v_mfma_f32_16x16x32_bf16 v[52:55], v[148:151], v[190:193], v[52:55]
	v_mfma_f32_16x16x32_bf16 v[48:51], v[156:159], v[190:193], v[48:51]
	v_mfma_f32_16x16x32_bf16 v[44:47], v[148:151], v[198:201], v[44:47]
	v_mfma_f32_16x16x32_bf16 v[40:43], v[156:159], v[198:201], v[40:43]
	v_mfma_f32_16x16x32_bf16 v[36:39], v[148:151], v[216:219], v[36:39]
	v_mfma_f32_16x16x32_bf16 v[32:35], v[156:159], v[216:219], v[32:35]
	s_setprio 0
	s_barrier
; #define PG8_STAGE(bufoff, gbase, voff) do { _Pragma("unroll") for (int _i = 0; _i < 2; ++_i) \
;         __builtin_amdgcn_global_load_lds((const unsigned*)((const char*)(gbase) + (voff)[_i]), (LAS unsigned*)(lds + (bufoff) + ldsw + _i * 8192), 16, 0, 0); } while (0)
; #define PG8_LDA(dst, b, h) do { _Pragma("unroll") for (int m = 0; m < 4; ++m) _Pragma("unroll") for (int k = 0; k < 2; ++k) dst[m][k] = *(const LAS bf16x8*)(lds + PG8_SA(b, h) + aoff + m * 2048 + k * 1024); } while (0)
; #define PG8_MMA(ai, bj, At, Bt) do { __builtin_amdgcn_s_setprio(1); _Pragma("unroll") for (int m = 0; m < 4; ++m) _Pragma("unroll") for (int n = 0; n < 2; ++n) _Pragma("unroll") for (int k = 0; k < 2; ++k) \
;         acc[ai][bj][m][n] = __builtin_amdgcn_mfma_f32_16x16x32_bf16(Bt[n][k], At[m][k], acc[ai][bj][m][n], 0, 0, 0); __builtin_amdgcn_s_setprio(0); } while (0)
; #define PG8_WAIT_V(n) asm volatile("s_waitcnt vmcnt(" #n ")" ::: "memory")
; #define PG8_WAIT_L(n) asm volatile("s_waitcnt lgkmcnt(" #n ")" ::: "memory")
; #define PG8_BAR __builtin_amdgcn_s_barrier()
; #define PG8_SCHED __builtin_amdgcn_sched_barrier(0)
; template <class Epi, class Sched>
; __device__ __forceinline__ void gemm_phase(LAS unsigned char* lds, const Gemm g, const Sched& S, const Epi& E, const int wave_s) {
;     ...
;             PG8_LDA(At, 1, 1); PG8_STAGE(PG8_SB(1, 0), b3, voffB); PG8_STAGE(PG8_SB(1, 1), b3 + hstepB, voffB); PG8_STAGE(PG8_SA(1, 0), a3, voffA);
;             PG8_WAIT_V(8); PG8_WAIT_L(0); PG8_BAR; PG8_MMA(1, 0, At, B0); PG8_MMA(1, 1, At, B1); PG8_BAR; PG8_SCHED;
;         }
;         if (wr == 0) PG8_BAR;
	s_add_i32 s42, s55, s81
	v_lshl_add_u64 v[206:207], v[206:207], 0, s[22:23]
	s_mov_b32 m0, s42
	ds_read_b128 v[160:163], v214 offset:49152
	ds_read_b128 v[164:167], v214 offset:50176
	ds_read_b128 v[186:189], v214 offset:51200
	ds_read_b128 v[190:193], v214 offset:52224
	ds_read_b128 v[194:197], v214 offset:53248
	ds_read_b128 v[198:201], v214 offset:54272
	ds_read_b128 v[202:205], v214 offset:55296
	ds_read_b128 v[216:219], v214 offset:56320
	global_load_lds_dwordx4 v[206:207], off
	s_add_i32 m0, s42, 0x2000
	s_add_u32 s4, s4, 0x40080
	v_lshl_add_u64 v[206:207], v[220:221], 0, s[22:23]
	s_addc_u32 s5, s5, 0
	s_add_i32 s42, s56, s81
	global_load_lds_dwordx4 v[206:207], off
	v_lshl_add_u64 v[206:207], s[4:5], 0, v[170:171]
	s_mov_b32 m0, s42
	s_nop 0
	global_load_lds_dwordx4 v[206:207], off
	v_lshl_add_u64 v[206:207], s[4:5], 0, v[174:175]
	s_add_i32 m0, s42, 0x2000
	s_nop 0
	global_load_lds_dwordx4 v[206:207], off
	v_lshl_add_u64 v[206:207], v[222:223], 0, s[22:23]
	s_mov_b32 m0, s47
	s_nop 0
	global_load_lds_dwordx4 v[206:207], off
	v_lshl_add_u64 v[206:207], v[224:225], 0, s[22:23]
	s_mov_b32 m0, s48
	s_nop 0
	global_load_lds_dwordx4 v[206:207], off
	s_waitcnt vmcnt(8) lgkmcnt(0)
	s_setprio 1
	s_barrier
	v_mfma_f32_16x16x32_bf16 v[92:95], v[100:103], v[160:163], v[92:95]
	v_mfma_f32_16x16x32_bf16 v[88:91], v[136:139], v[160:163], v[88:91]
	v_mfma_f32_16x16x32_bf16 v[84:87], v[100:103], v[186:189], v[84:87]
	v_mfma_f32_16x16x32_bf16 v[80:83], v[136:139], v[186:189], v[80:83]
	v_mfma_f32_16x16x32_bf16 v[76:79], v[100:103], v[194:197], v[76:79]
	v_mfma_f32_16x16x32_bf16 v[72:75], v[136:139], v[194:197], v[72:75]
	v_mfma_f32_16x16x32_bf16 v[68:71], v[100:103], v[202:205], v[68:71]
	v_mfma_f32_16x16x32_bf16 v[64:67], v[136:139], v[202:205], v[64:67]
	v_mfma_f32_16x16x32_bf16 v[92:95], v[108:111], v[164:167], v[92:95]
	v_mfma_f32_16x16x32_bf16 v[88:91], v[140:143], v[164:167], v[88:91]
	v_mfma_f32_16x16x32_bf16 v[84:87], v[108:111], v[190:193], v[84:87]
	v_mfma_f32_16x16x32_bf16 v[80:83], v[140:143], v[190:193], v[80:83]
	v_mfma_f32_16x16x32_bf16 v[76:79], v[108:111], v[198:201], v[76:79]
	v_mfma_f32_16x16x32_bf16 v[72:75], v[140:143], v[198:201], v[72:75]
	v_mfma_f32_16x16x32_bf16 v[68:71], v[108:111], v[216:219], v[68:71]
	v_mfma_f32_16x16x32_bf16 v[64:67], v[140:143], v[216:219], v[64:67]
	s_setprio 0
	s_setprio 1
	v_mfma_f32_16x16x32_bf16 v[28:31], v[144:147], v[160:163], v[28:31]
	v_mfma_f32_16x16x32_bf16 v[24:27], v[152:155], v[160:163], v[24:27]
	v_mfma_f32_16x16x32_bf16 v[20:23], v[144:147], v[186:189], v[20:23]
	v_mfma_f32_16x16x32_bf16 v[16:19], v[152:155], v[186:189], v[16:19]
	v_mfma_f32_16x16x32_bf16 v[12:15], v[144:147], v[194:197], v[12:15]
	v_mfma_f32_16x16x32_bf16 v[8:11], v[152:155], v[194:197], v[8:11]
	v_mfma_f32_16x16x32_bf16 v[4:7], v[144:147], v[202:205], v[4:7]
	v_mfma_f32_16x16x32_bf16 v[0:3], v[152:155], v[202:205], v[0:3]
	v_mfma_f32_16x16x32_bf16 v[28:31], v[148:151], v[164:167], v[28:31]
	v_mfma_f32_16x16x32_bf16 v[24:27], v[156:159], v[164:167], v[24:27]
	v_mfma_f32_16x16x32_bf16 v[20:23], v[148:151], v[190:193], v[20:23]
	v_mfma_f32_16x16x32_bf16 v[16:19], v[156:159], v[190:193], v[16:19]
	v_mfma_f32_16x16x32_bf16 v[12:15], v[148:151], v[198:201], v[12:15]
	v_mfma_f32_16x16x32_bf16 v[8:11], v[156:159], v[198:201], v[8:11]
	v_mfma_f32_16x16x32_bf16 v[4:7], v[148:151], v[216:219], v[4:7]
	v_mfma_f32_16x16x32_bf16 v[0:3], v[156:159], v[216:219], v[0:3]
	s_setprio 0
	s_barrier
	s_add_i32 s54, s54, 2
	s_add_u32 s40, s40, 0x100
	s_addc_u32 s41, s41, 0
	s_add_u32 s39, s39, 0x100
	s_addc_u32 s53, s53, 0
	s_cmp_gt_u32 s54, 13
	s_cbranch_scc0 .LBB0_860
	s_and_b64 vcc, exec, s[24:25]
	s_cbranch_vccz .LBB0_863
	s_barrier

; #define PG8_STAGE(bufoff, gbase, voff) do { _Pragma("unroll") for (int _i = 0; _i < 2; ++_i) \
;         __builtin_amdgcn_global_load_lds((const unsigned*)((const char*)(gbase) + (voff)[_i]), (LAS unsigned*)(lds + (bufoff) + ldsw + _i * 8192), 16, 0, 0); } while (0)
; #define PG8_LDA(dst, b, h) do { _Pragma("unroll") for (int m = 0; m < 4; ++m) _Pragma("unroll") for (int k = 0; k < 2; ++k) dst[m][k] = *(const LAS bf16x8*)(lds + PG8_SA(b, h) + aoff + m * 2048 + k * 1024); } while (0)
; #define PG8_LDB(dst, b, h) do { _Pragma("unroll") for (int n = 0; n < 2; ++n) _Pragma("unroll") for (int k = 0; k < 2; ++k) dst[n][k] = *(const LAS bf16x8*)(lds + PG8_SB(b, h) + boff + n * 2048 + k * 1024); } while (0)
; #define PG8_MMA(ai, bj, At, Bt) do { __builtin_amdgcn_s_setprio(1); _Pragma("unroll") for (int m = 0; m < 4; ++m) _Pragma("unroll") for (int n = 0; n < 2; ++n) _Pragma("unroll") for (int k = 0; k < 2; ++k) \
;         acc[ai][bj][m][n] = __builtin_amdgcn_mfma_f32_16x16x32_bf16(Bt[n][k], At[m][k], acc[ai][bj][m][n], 0, 0, 0); __builtin_amdgcn_s_setprio(0); } while (0)
; #define PG8_WAIT_V(n) asm volatile("s_waitcnt vmcnt(" #n ")" ::: "memory")
; #define PG8_WAIT_L(n) asm volatile("s_waitcnt lgkmcnt(" #n ")" ::: "memory")
; #define PG8_BAR __builtin_amdgcn_s_barrier()
; #define PG8_SCHED __builtin_amdgcn_sched_barrier(0)
; template <class Epi, class Sched>
; __device__ __forceinline__ void gemm_phase(LAS unsigned char* lds, const Gemm g, const Sched& S, const Epi& E, const int wave_s) {
;     ...
;             const bool last = (t == nt - 2);
;             const char* a1 = cA + (size_t)(t + 1) * kstep;
;             const char* a2 = last ? nA : cA + (size_t)(t + 2) * kstep; const char* b2 = last ? nB : cB + (size_t)(t + 2) * kstep;
;             const char* a3 = a2 + kstep; const char* b3 = b2 + kstep;
;             PG8_LDB(B0, 0, 0); PG8_LDB(B1, 0, 1); PG8_SCHED; PG8_LDA(At, 0, 0); PG8_STAGE(PG8_SA(1, 1), a1 + hstepA, voffA);
;             PG8_WAIT_V(8); PG8_WAIT_L(0); PG8_BAR; PG8_MMA(0, 0, At, B0); PG8_MMA(0, 1, At, B1); PG8_BAR; PG8_SCHED;
;             PG8_LDA(At, 0, 1); PG8_STAGE(PG8_SB(0, 0), b2, voffB); PG8_STAGE(PG8_SB(0, 1), b2 + hstepB, voffB); PG8_STAGE(PG8_SA(0, 0), a2, voffA);
.LBB0_1024:
	s_add_u32 s48, s64, s46
	s_addc_u32 s49, s65, s47
	s_add_u32 s48, s48, 0x99a5200
	s_addc_u32 s49, s49, 0
	s_add_u32 s73, s70, s46
	s_addc_u32 s74, s71, s47
	s_add_i32 s75, 0, 0x10000
	s_cmpk_eq_i32 s46, 0x700
	s_cselect_b32 s51, s11, s49
	s_cselect_b32 s50, s10, s48
	v_add_u32_e32 v128, s75, v178
	s_cselect_b32 s49, s68, s74
	s_cselect_b32 s48, s69, s73
	s_add_i32 s73, 0, 0x14000
	ds_read_b128 v[170:173], v128
	ds_read_b128 v[182:185], v128 offset:1024
	ds_read_b128 v[186:189], v128 offset:2048
	ds_read_b128 v[190:193], v128 offset:3072
	v_add_u32_e32 v128, s73, v178
	ds_read_b128 v[194:197], v128
	ds_read_b128 v[198:201], v128 offset:1024
	ds_read_b128 v[202:205], v128 offset:2048
	ds_read_b128 v[206:209], v128 offset:3072
	v_lshl_add_u64 v[242:243], v[166:167], 0, s[46:47]
	s_add_i32 m0, s52, 0xc000
	ds_read_b128 v[210:213], v180
	ds_read_b128 v[214:217], v180 offset:1024
	ds_read_b128 v[218:221], v180 offset:2048
	ds_read_b128 v[222:225], v180 offset:3072
	ds_read_b128 v[226:229], v180 offset:4096
	ds_read_b128 v[230:233], v180 offset:5120
	ds_read_b128 v[234:237], v180 offset:6144
	ds_read_b128 v[238:241], v180 offset:7168
	global_load_lds_dwordx4 v[242:243], off
	v_lshl_add_u64 v[242:243], v[168:169], 0, s[46:47]
	s_add_i32 m0, s52, 0xe000
	s_nop 0
	global_load_lds_dwordx4 v[242:243], off
	s_waitcnt vmcnt(8) lgkmcnt(0)
	s_setprio 1
	s_barrier
	v_mfma_f32_16x16x32_bf16 v[124:127], v[170:173], v[210:213], v[124:127]
	v_mfma_f32_16x16x32_bf16 v[120:123], v[186:189], v[210:213], v[120:123]
	v_mfma_f32_16x16x32_bf16 v[116:119], v[170:173], v[218:221], v[116:119]
	v_mfma_f32_16x16x32_bf16 v[112:115], v[186:189], v[218:221], v[112:115]
	v_mfma_f32_16x16x32_bf16 v[108:111], v[170:173], v[226:229], v[108:111]
	v_mfma_f32_16x16x32_bf16 v[100:103], v[186:189], v[226:229], v[100:103]
	v_mfma_f32_16x16x32_bf16 v[92:95], v[170:173], v[234:237], v[92:95]
	v_mfma_f32_16x16x32_bf16 v[84:87], v[186:189], v[234:237], v[84:87]
	v_mfma_f32_16x16x32_bf16 v[124:127], v[182:185], v[214:217], v[124:127]
	v_mfma_f32_16x16x32_bf16 v[120:123], v[190:193], v[214:217], v[120:123]
	v_mfma_f32_16x16x32_bf16 v[116:119], v[182:185], v[222:225], v[116:119]
	v_mfma_f32_16x16x32_bf16 v[112:115], v[190:193], v[222:225], v[112:115]
	v_mfma_f32_16x16x32_bf16 v[108:111], v[182:185], v[230:233], v[108:111]
	v_mfma_f32_16x16x32_bf16 v[100:103], v[190:193], v[230:233], v[100:103]
	v_mfma_f32_16x16x32_bf16 v[92:95], v[182:185], v[238:241], v[92:95]
	v_mfma_f32_16x16x32_bf16 v[84:87], v[190:193], v[238:241], v[84:87]
	s_setprio 0
	s_setprio 1
	v_mfma_f32_16x16x32_bf16 v[104:107], v[194:197], v[210:213], v[104:107]
	v_mfma_f32_16x16x32_bf16 v[96:99], v[202:205], v[210:213], v[96:99]
	v_mfma_f32_16x16x32_bf16 v[88:91], v[194:197], v[218:221], v[88:91]
	v_mfma_f32_16x16x32_bf16 v[80:83], v[202:205], v[218:221], v[80:83]
	v_mfma_f32_16x16x32_bf16 v[76:79], v[194:197], v[226:229], v[76:79]
	v_mfma_f32_16x16x32_bf16 v[72:75], v[202:205], v[226:229], v[72:75]
	v_mfma_f32_16x16x32_bf16 v[68:71], v[194:197], v[234:237], v[68:71]
	v_mfma_f32_16x16x32_bf16 v[64:67], v[202:205], v[234:237], v[64:67]
	v_mfma_f32_16x16x32_bf16 v[104:107], v[198:201], v[214:217], v[104:107]
	v_mfma_f32_16x16x32_bf16 v[96:99], v[206:209], v[214:217], v[96:99]
	v_mfma_f32_16x16x32_bf16 v[88:91], v[198:201], v[222:225], v[88:91]
	v_mfma_f32_16x16x32_bf16 v[80:83], v[206:209], v[222:225], v[80:83]
	v_mfma_f32_16x16x32_bf16 v[76:79], v[198:201], v[230:233], v[76:79]
	v_mfma_f32_16x16x32_bf16 v[72:75], v[206:209], v[230:233], v[72:75]
	v_mfma_f32_16x16x32_bf16 v[68:71], v[198:201], v[238:241], v[68:71]
	v_mfma_f32_16x16x32_bf16 v[64:67], v[206:209], v[238:241], v[64:67]
	s_setprio 0
	s_barrier
	s_add_i32 s74, s75, s81
	v_lshl_add_u64 v[242:243], s[48:49], 0, v[130:131]
	s_mov_b32 m0, s74
	ds_read_b128 v[210:213], v180 offset:16384
	ds_read_b128 v[214:217], v180 offset:17408
	ds_read_b128 v[218:221], v180 offset:18432
	ds_read_b128 v[222:225], v180 offset:19456
	ds_read_b128 v[226:229], v180 offset:20480
	ds_read_b128 v[230:233], v180 offset:21504
	ds_read_b128 v[234:237], v180 offset:22528
	ds_read_b128 v[238:241], v180 offset:23552
	global_load_lds_dwordx4 v[242:243], off
	s_add_i32 m0, s74, 0x2000
	s_add_u32 s74, s48, 0x40000
	v_lshl_add_u64 v[244:245], s[48:49], 0, v[132:133]
	s_addc_u32 s75, s49, 0
	s_add_i32 s73, s73, s81
	global_load_lds_dwordx4 v[244:245], off
	v_lshl_add_u64 v[246:247], s[74:75], 0, v[130:131]
	s_mov_b32 m0, s73
	v_lshl_add_u64 v[248:249], s[50:51], 0, v[132:133]
	global_load_lds_dwordx4 v[246:247], off
	v_lshl_add_u64 v[246:247], s[74:75], 0, v[132:133]
	s_add_i32 m0, s73, 0x2000
	s_nop 0
	global_load_lds_dwordx4 v[246:247], off
	v_lshl_add_u64 v[246:247], s[50:51], 0, v[130:131]
	s_mov_b32 m0, s52
	s_nop 0
	global_load_lds_dwordx4 v[246:247], off
	s_mov_b32 m0, s57
	s_nop 0
	global_load_lds_dwordx4 v[248:249], off
	s_waitcnt vmcnt(8) lgkmcnt(0)
	s_setprio 1
	s_barrier
; #define PG8_STAGE(bufoff, gbase, voff) do { _Pragma("unroll") for (int _i = 0; _i < 2; ++_i) \
;         __builtin_amdgcn_global_load_lds((const unsigned*)((const char*)(gbase) + (voff)[_i]), (LAS unsigned*)(lds + (bufoff) + ldsw + _i * 8192), 16, 0, 0); } while (0)
; #define PG8_LDA(dst, b, h) do { _Pragma("unroll") for (int m = 0; m < 4; ++m) _Pragma("unroll") for (int k = 0; k < 2; ++k) dst[m][k] = *(const LAS bf16x8*)(lds + PG8_SA(b, h) + aoff + m * 2048 + k * 1024); } while (0)
; #define PG8_LDB(dst, b, h) do { _Pragma("unroll") for (int n = 0; n < 2; ++n) _Pragma("unroll") for (int k = 0; k < 2; ++k) dst[n][k] = *(const LAS bf16x8*)(lds + PG8_SB(b, h) + boff + n * 2048 + k * 1024); } while (0)
; #define PG8_MMA(ai, bj, At, Bt) do { __builtin_amdgcn_s_setprio(1); _Pragma("unroll") for (int m = 0; m < 4; ++m) _Pragma("unroll") for (int n = 0; n < 2; ++n) _Pragma("unroll") for (int k = 0; k < 2; ++k) \
;         acc[ai][bj][m][n] = __builtin_amdgcn_mfma_f32_16x16x32_bf16(Bt[n][k], At[m][k], acc[ai][bj][m][n], 0, 0, 0); __builtin_amdgcn_s_setprio(0); } while (0)
; #define PG8_WAIT_V(n) asm volatile("s_waitcnt vmcnt(" #n ")" ::: "memory")
; #define PG8_WAIT_L(n) asm volatile("s_waitcnt lgkmcnt(" #n ")" ::: "memory")
; #define PG8_BAR __builtin_amdgcn_s_barrier()
; #define PG8_SCHED __builtin_amdgcn_sched_barrier(0)
; template <class Epi, class Sched>
; __device__ __forceinline__ void gemm_phase(LAS unsigned char* lds, const Gemm g, const Sched& S, const Epi& E, const int wave_s) {
;     ...
;             PG8_WAIT_V(8); PG8_WAIT_L(0); PG8_BAR; PG8_MMA(1, 0, At, B0); PG8_MMA(1, 1, At, B1); PG8_BAR; PG8_SCHED;
;             PG8_LDB(B0, 1, 0); PG8_LDB(B1, 1, 1); PG8_SCHED; PG8_LDA(At, 1, 0); PG8_STAGE(PG8_SA(0, 1), a2 + hstepA, voffA);
;             PG8_WAIT_V(8); PG8_WAIT_L(0); PG8_BAR; PG8_MMA(0, 0, At, B0); PG8_MMA(0, 1, At, B1); PG8_BAR; PG8_SCHED;
	v_mfma_f32_16x16x32_bf16 v[60:63], v[170:173], v[210:213], v[60:63]
	v_mfma_f32_16x16x32_bf16 v[56:59], v[186:189], v[210:213], v[56:59]
	v_mfma_f32_16x16x32_bf16 v[52:55], v[170:173], v[218:221], v[52:55]
	v_mfma_f32_16x16x32_bf16 v[48:51], v[186:189], v[218:221], v[48:51]
	v_mfma_f32_16x16x32_bf16 v[44:47], v[170:173], v[226:229], v[44:47]
	v_mfma_f32_16x16x32_bf16 v[36:39], v[186:189], v[226:229], v[36:39]
	v_mfma_f32_16x16x32_bf16 v[28:31], v[170:173], v[234:237], v[28:31]
	v_mfma_f32_16x16x32_bf16 v[20:23], v[186:189], v[234:237], v[20:23]
	v_mfma_f32_16x16x32_bf16 v[60:63], v[182:185], v[214:217], v[60:63]
	v_mfma_f32_16x16x32_bf16 v[56:59], v[190:193], v[214:217], v[56:59]
	v_mfma_f32_16x16x32_bf16 v[52:55], v[182:185], v[222:225], v[52:55]
	v_mfma_f32_16x16x32_bf16 v[48:51], v[190:193], v[222:225], v[48:51]
	v_mfma_f32_16x16x32_bf16 v[44:47], v[182:185], v[230:233], v[44:47]
	v_mfma_f32_16x16x32_bf16 v[36:39], v[190:193], v[230:233], v[36:39]
	v_mfma_f32_16x16x32_bf16 v[28:31], v[182:185], v[238:241], v[28:31]
	v_mfma_f32_16x16x32_bf16 v[20:23], v[190:193], v[238:241], v[20:23]
	s_setprio 0
	s_setprio 1
	v_mfma_f32_16x16x32_bf16 v[40:43], v[194:197], v[210:213], v[40:43]
	v_mfma_f32_16x16x32_bf16 v[32:35], v[202:205], v[210:213], v[32:35]
	v_mfma_f32_16x16x32_bf16 v[24:27], v[194:197], v[218:221], v[24:27]
	v_mfma_f32_16x16x32_bf16 v[16:19], v[202:205], v[218:221], v[16:19]
	v_mfma_f32_16x16x32_bf16 v[12:15], v[194:197], v[226:229], v[12:15]
	v_mfma_f32_16x16x32_bf16 v[8:11], v[202:205], v[226:229], v[8:11]
	v_mfma_f32_16x16x32_bf16 v[4:7], v[194:197], v[234:237], v[4:7]
	v_mfma_f32_16x16x32_bf16 v[0:3], v[202:205], v[234:237], v[0:3]
	v_mfma_f32_16x16x32_bf16 v[40:43], v[198:201], v[214:217], v[40:43]
	v_mfma_f32_16x16x32_bf16 v[32:35], v[206:209], v[214:217], v[32:35]
	v_mfma_f32_16x16x32_bf16 v[24:27], v[198:201], v[222:225], v[24:27]
	v_mfma_f32_16x16x32_bf16 v[16:19], v[206:209], v[222:225], v[16:19]
	v_mfma_f32_16x16x32_bf16 v[12:15], v[198:201], v[230:233], v[12:15]
	v_mfma_f32_16x16x32_bf16 v[8:11], v[206:209], v[230:233], v[8:11]
	v_mfma_f32_16x16x32_bf16 v[4:7], v[198:201], v[238:241], v[4:7]
	v_mfma_f32_16x16x32_bf16 v[0:3], v[206:209], v[238:241], v[0:3]
	s_setprio 0
	s_barrier
	s_add_i32 s73, 0, 0x18000
	v_add_u32_e32 v128, s73, v178
	s_add_i32 s74, 0, 0x1c000
	ds_read_b128 v[170:173], v128
	ds_read_b128 v[182:185], v128 offset:1024
	ds_read_b128 v[186:189], v128 offset:2048
	ds_read_b128 v[190:193], v128 offset:3072
	v_add_u32_e32 v128, s74, v178
	ds_read_b128 v[194:197], v128
	ds_read_b128 v[198:201], v128 offset:1024
	ds_read_b128 v[202:205], v128 offset:2048
	ds_read_b128 v[206:209], v128 offset:3072
	s_add_u32 s50, s50, 0x40000
	s_addc_u32 s51, s51, 0
	s_mov_b32 m0, s58
	v_lshl_add_u64 v[250:251], s[50:51], 0, v[130:131]
	ds_read_b128 v[210:213], v180 offset:32768
	ds_read_b128 v[214:217], v180 offset:33792
	ds_read_b128 v[218:221], v180 offset:34816
	ds_read_b128 v[222:225], v180 offset:35840
	ds_read_b128 v[226:229], v180 offset:36864
	ds_read_b128 v[230:233], v180 offset:37888
	ds_read_b128 v[234:237], v180 offset:38912
	ds_read_b128 v[238:241], v180 offset:39936
	global_load_lds_dwordx4 v[250:251], off
	v_lshl_add_u64 v[250:251], s[50:51], 0, v[132:133]
	s_mov_b32 m0, s59
	s_nop 0
	global_load_lds_dwordx4 v[250:251], off
	s_waitcnt vmcnt(8) lgkmcnt(0)
	s_setprio 1
	s_barrier
	v_mfma_f32_16x16x32_bf16 v[124:127], v[170:173], v[210:213], v[124:127]
	v_mfma_f32_16x16x32_bf16 v[120:123], v[186:189], v[210:213], v[120:123]
	v_mfma_f32_16x16x32_bf16 v[116:119], v[170:173], v[218:221], v[116:119]
	v_mfma_f32_16x16x32_bf16 v[112:115], v[186:189], v[218:221], v[112:115]
	v_mfma_f32_16x16x32_bf16 v[108:111], v[170:173], v[226:229], v[108:111]
	v_mfma_f32_16x16x32_bf16 v[100:103], v[186:189], v[226:229], v[100:103]
	v_mfma_f32_16x16x32_bf16 v[92:95], v[170:173], v[234:237], v[92:95]
	v_mfma_f32_16x16x32_bf16 v[84:87], v[186:189], v[234:237], v[84:87]
	v_mfma_f32_16x16x32_bf16 v[124:127], v[182:185], v[214:217], v[124:127]
	v_mfma_f32_16x16x32_bf16 v[120:123], v[190:193], v[214:217], v[120:123]
	v_mfma_f32_16x16x32_bf16 v[116:119], v[182:185], v[222:225], v[116:119]
	v_mfma_f32_16x16x32_bf16 v[112:115], v[190:193], v[222:225], v[112:115]
	v_mfma_f32_16x16x32_bf16 v[108:111], v[182:185], v[230:233], v[108:111]
	v_mfma_f32_16x16x32_bf16 v[100:103], v[190:193], v[230:233], v[100:103]
	v_mfma_f32_16x16x32_bf16 v[92:95], v[182:185], v[238:241], v[92:95]
	v_mfma_f32_16x16x32_bf16 v[84:87], v[190:193], v[238:241], v[84:87]
	s_setprio 0
	s_setprio 1
	v_mfma_f32_16x16x32_bf16 v[104:107], v[194:197], v[210:213], v[104:107]
	v_mfma_f32_16x16x32_bf16 v[96:99], v[202:205], v[210:213], v[96:99]
	v_mfma_f32_16x16x32_bf16 v[88:91], v[194:197], v[218:221], v[88:91]
	v_mfma_f32_16x16x32_bf16 v[80:83], v[202:205], v[218:221], v[80:83]
	v_mfma_f32_16x16x32_bf16 v[76:79], v[194:197], v[226:229], v[76:79]
	v_mfma_f32_16x16x32_bf16 v[72:75], v[202:205], v[226:229], v[72:75]
	v_mfma_f32_16x16x32_bf16 v[68:71], v[194:197], v[234:237], v[68:71]
	v_mfma_f32_16x16x32_bf16 v[64:67], v[202:205], v[234:237], v[64:67]
	v_mfma_f32_16x16x32_bf16 v[104:107], v[198:201], v[214:217], v[104:107]
	v_mfma_f32_16x16x32_bf16 v[96:99], v[206:209], v[214:217], v[96:99]
	v_mfma_f32_16x16x32_bf16 v[88:91], v[198:201], v[222:225], v[88:91]
	v_mfma_f32_16x16x32_bf16 v[80:83], v[206:209], v[222:225], v[80:83]
	v_mfma_f32_16x16x32_bf16 v[76:79], v[198:201], v[230:233], v[76:79]
	v_mfma_f32_16x16x32_bf16 v[72:75], v[206:209], v[230:233], v[72:75]
	v_mfma_f32_16x16x32_bf16 v[68:71], v[198:201], v[238:241], v[68:71]
	v_mfma_f32_16x16x32_bf16 v[64:67], v[206:209], v[238:241], v[64:67]
	s_setprio 0
	s_barrier
; #define PG8_STAGE(bufoff, gbase, voff) do { _Pragma("unroll") for (int _i = 0; _i < 2; ++_i) \
;         __builtin_amdgcn_global_load_lds((const unsigned*)((const char*)(gbase) + (voff)[_i]), (LAS unsigned*)(lds + (bufoff) + ldsw + _i * 8192), 16, 0, 0); } while (0)
; #define PG8_LDA(dst, b, h) do { _Pragma("unroll") for (int m = 0; m < 4; ++m) _Pragma("unroll") for (int k = 0; k < 2; ++k) dst[m][k] = *(const LAS bf16x8*)(lds + PG8_SA(b, h) + aoff + m * 2048 + k * 1024); } while (0)
; #define PG8_MMA(ai, bj, At, Bt) do { __builtin_amdgcn_s_setprio(1); _Pragma("unroll") for (int m = 0; m < 4; ++m) _Pragma("unroll") for (int n = 0; n < 2; ++n) _Pragma("unroll") for (int k = 0; k < 2; ++k) \
;         acc[ai][bj][m][n] = __builtin_amdgcn_mfma_f32_16x16x32_bf16(Bt[n][k], At[m][k], acc[ai][bj][m][n], 0, 0, 0); __builtin_amdgcn_s_setprio(0); } while (0)
; #define PG8_WAIT_V(n) asm volatile("s_waitcnt vmcnt(" #n ")" ::: "memory")
; #define PG8_WAIT_L(n) asm volatile("s_waitcnt lgkmcnt(" #n ")" ::: "memory")
; #define PG8_BAR __builtin_amdgcn_s_barrier()
; #define PG8_SCHED __builtin_amdgcn_sched_barrier(0)
; template <class Epi, class Sched>
; __device__ __forceinline__ void gemm_phase(LAS unsigned char* lds, const Gemm g, const Sched& S, const Epi& E, const int wave_s) {
;     ...
;             PG8_LDA(At, 1, 1); PG8_STAGE(PG8_SB(1, 0), b3, voffB); PG8_STAGE(PG8_SB(1, 1), b3 + hstepB, voffB); PG8_STAGE(PG8_SA(1, 0), a3, voffA);
;             PG8_WAIT_V(8); PG8_WAIT_L(0); PG8_BAR; PG8_MMA(1, 0, At, B0); PG8_MMA(1, 1, At, B1); PG8_BAR; PG8_SCHED;
;         }
;         if (wr == 0) PG8_BAR;
	s_add_i32 s50, s73, s81
	v_lshl_add_u64 v[242:243], v[242:243], 0, s[22:23]
	s_mov_b32 m0, s50
	ds_read_b128 v[210:213], v180 offset:49152
	ds_read_b128 v[214:217], v180 offset:50176
	ds_read_b128 v[218:221], v180 offset:51200
	ds_read_b128 v[222:225], v180 offset:52224
	ds_read_b128 v[226:229], v180 offset:53248
	ds_read_b128 v[230:233], v180 offset:54272
	ds_read_b128 v[234:237], v180 offset:55296
	ds_read_b128 v[238:241], v180 offset:56320
	global_load_lds_dwordx4 v[242:243], off
	s_add_i32 m0, s50, 0x2000
	s_add_u32 s48, s48, 0x40080
	v_lshl_add_u64 v[242:243], v[244:245], 0, s[22:23]
	s_addc_u32 s49, s49, 0
	s_add_i32 s50, s74, s81
	global_load_lds_dwordx4 v[242:243], off
	v_lshl_add_u64 v[242:243], s[48:49], 0, v[130:131]
	s_mov_b32 m0, s50
	s_nop 0
	global_load_lds_dwordx4 v[242:243], off
	v_lshl_add_u64 v[242:243], s[48:49], 0, v[132:133]
	s_add_i32 m0, s50, 0x2000
	s_nop 0
	global_load_lds_dwordx4 v[242:243], off
	v_lshl_add_u64 v[242:243], v[246:247], 0, s[22:23]
	s_mov_b32 m0, s20
	s_nop 0
	global_load_lds_dwordx4 v[242:243], off
	v_lshl_add_u64 v[242:243], v[248:249], 0, s[22:23]
	s_mov_b32 m0, s63
	s_nop 0
	global_load_lds_dwordx4 v[242:243], off
	s_waitcnt vmcnt(8) lgkmcnt(0)
	s_setprio 1
	s_barrier
	v_mfma_f32_16x16x32_bf16 v[60:63], v[170:173], v[210:213], v[60:63]
	v_mfma_f32_16x16x32_bf16 v[56:59], v[186:189], v[210:213], v[56:59]
	v_mfma_f32_16x16x32_bf16 v[52:55], v[170:173], v[218:221], v[52:55]
	v_mfma_f32_16x16x32_bf16 v[48:51], v[186:189], v[218:221], v[48:51]
	v_mfma_f32_16x16x32_bf16 v[44:47], v[170:173], v[226:229], v[44:47]
	v_mfma_f32_16x16x32_bf16 v[36:39], v[186:189], v[226:229], v[36:39]
	v_mfma_f32_16x16x32_bf16 v[28:31], v[170:173], v[234:237], v[28:31]
	v_mfma_f32_16x16x32_bf16 v[20:23], v[186:189], v[234:237], v[20:23]
	v_mfma_f32_16x16x32_bf16 v[60:63], v[182:185], v[214:217], v[60:63]
	v_mfma_f32_16x16x32_bf16 v[56:59], v[190:193], v[214:217], v[56:59]
	v_mfma_f32_16x16x32_bf16 v[52:55], v[182:185], v[222:225], v[52:55]
	v_mfma_f32_16x16x32_bf16 v[48:51], v[190:193], v[222:225], v[48:51]
	v_mfma_f32_16x16x32_bf16 v[44:47], v[182:185], v[230:233], v[44:47]
	v_mfma_f32_16x16x32_bf16 v[36:39], v[190:193], v[230:233], v[36:39]
	v_mfma_f32_16x16x32_bf16 v[28:31], v[182:185], v[238:241], v[28:31]
	v_mfma_f32_16x16x32_bf16 v[20:23], v[190:193], v[238:241], v[20:23]
	s_setprio 0
	s_setprio 1
	v_mfma_f32_16x16x32_bf16 v[40:43], v[194:197], v[210:213], v[40:43]
	v_mfma_f32_16x16x32_bf16 v[32:35], v[202:205], v[210:213], v[32:35]
	v_mfma_f32_16x16x32_bf16 v[24:27], v[194:197], v[218:221], v[24:27]
	v_mfma_f32_16x16x32_bf16 v[16:19], v[202:205], v[218:221], v[16:19]
	v_mfma_f32_16x16x32_bf16 v[12:15], v[194:197], v[226:229], v[12:15]
	v_mfma_f32_16x16x32_bf16 v[8:11], v[202:205], v[226:229], v[8:11]
	v_mfma_f32_16x16x32_bf16 v[4:7], v[194:197], v[234:237], v[4:7]
	v_mfma_f32_16x16x32_bf16 v[0:3], v[202:205], v[234:237], v[0:3]
	v_mfma_f32_16x16x32_bf16 v[40:43], v[198:201], v[214:217], v[40:43]
	v_mfma_f32_16x16x32_bf16 v[32:35], v[206:209], v[214:217], v[32:35]
	v_mfma_f32_16x16x32_bf16 v[24:27], v[198:201], v[222:225], v[24:27]
	v_mfma_f32_16x16x32_bf16 v[16:19], v[206:209], v[222:225], v[16:19]
	v_mfma_f32_16x16x32_bf16 v[12:15], v[198:201], v[230:233], v[12:15]
	v_mfma_f32_16x16x32_bf16 v[8:11], v[206:209], v[230:233], v[8:11]
	v_mfma_f32_16x16x32_bf16 v[4:7], v[198:201], v[238:241], v[4:7]
	v_mfma_f32_16x16x32_bf16 v[0:3], v[206:209], v[238:241], v[0:3]
	s_setprio 0
	s_barrier
	s_add_i32 s72, s72, 2
	s_add_u32 s46, s46, 0x100
	s_addc_u32 s47, s47, 0
	s_cmp_gt_u32 s72, 13
	s_cbranch_scc0 .LBB0_1024
	s_and_b64 vcc, exec, s[12:13]
	s_cbranch_vccz .LBB0_1027
	s_barrier
